# hand-written pool-phase main loop: wave-uniform units, batched double-buffered loads
# speedup vs baseline: 1.0234x; 1.0234x over previous
.LBB0_663:
	s_or_b64 exec, exec, s[0:1]
	v_readlane_b32 s6, v255, 10
	v_readlane_b32 s7, v255, 11
	s_mov_b64 s[0:1], -1
	s_and_b64 vcc, exec, s[6:7]
	s_waitcnt lgkmcnt(0)
	s_barrier
	s_cbranch_vccz .LBB0_717
	v_mov_b32_e32 v0, v232
	v_readlane_b32 s0, v254, 17
	s_lshl_b32 s21, s50, 7
	s_nop 0
	v_add_u32_e32 v96, s0, v0
	s_mov_b32 s0, 0x28000
	v_cmp_gt_i32_e32 vcc, s0, v96
	v_readlane_b32 s0, v254, 56
	s_nop 1
	v_lshl_add_u32 v97, v0, 3, s0
	s_and_saveexec_b64 s[6:7], vcc
	s_cbranch_execz .LBB0_705
	v_and_b32_e32 v48, 0xff, v96
	v_readfirstlane_b32 s49, v96
	v_lshlrev_b32_e32 v114, 5, v48
	v_lshlrev_b32_e32 v48, 4, v48
	s_nop 3
	s_bfe_u32 s0, s49, 0x20006
	s_lshl_b32 s41, 2, s0
	s_add_i32 s43, s41, -1
	s_bfe_u32 s0, s49, 0x60008
	s_lshl_b32 s98, s0, 5
	s_lshr_b32 s1, s49, 14
	s_lshl_b32 s42, s1, 11
	s_add_i32 s48, s98, 32
	s_add_i32 s0, s42, s98
	s_lshl_b32 s0, s0, 12
	s_add_u32 s22, s70, s0
	s_addc_u32 s23, s71, 0
	v_mov_b32_e32 v32, 0
	v_mov_b32_e32 v33, 0
	v_mov_b32_e32 v34, 0
	v_mov_b32_e32 v35, 0
	v_mov_b32_e32 v36, 0
	v_mov_b32_e32 v37, 0
	v_mov_b32_e32 v38, 0
	v_mov_b32_e32 v39, 0
	s_mov_b32 s40, s98
	s_add_i32 s0, s42, s40
	s_lshl_b32 s0, s0, 13
	s_add_u32 s8, s4, s0
	s_addc_u32 s9, s5, 0
	global_load_dwordx4 v[0:3], v48, s[8:9]
	s_add_u32 s8, s8, 0x2000
	s_addc_u32 s9, s9, 0
	global_load_dwordx4 v[4:7], v48, s[8:9]
	s_add_u32 s8, s8, 0x2000
	s_addc_u32 s9, s9, 0
	global_load_dwordx4 v[8:11], v48, s[8:9]
	s_add_u32 s8, s8, 0x2000
	s_addc_u32 s9, s9, 0
	global_load_dwordx4 v[12:15], v48, s[8:9]
	s_sub_i32 s1, s40, s43
	s_add_i32 s0, s1, 0
	s_max_i32 s0, s0, 0
	s_add_i32 s0, s0, s42
	s_lshl_b32 s0, s0, 13
	s_add_u32 s10, s4, s0
	s_addc_u32 s11, s5, 0
	global_load_dwordx4 v[16:19], v48, s[10:11]
	s_add_i32 s0, s1, 1
	s_max_i32 s0, s0, 0
	s_add_i32 s0, s0, s42
	s_lshl_b32 s0, s0, 13
	s_add_u32 s10, s4, s0
	s_addc_u32 s11, s5, 0
	global_load_dwordx4 v[20:23], v48, s[10:11]
	s_add_i32 s0, s1, 2
	s_max_i32 s0, s0, 0
	s_add_i32 s0, s0, s42
	s_lshl_b32 s0, s0, 13
	s_add_u32 s10, s4, s0
	s_addc_u32 s11, s5, 0
	global_load_dwordx4 v[24:27], v48, s[10:11]
	s_add_i32 s0, s1, 3
	s_max_i32 s0, s0, 0
	s_add_i32 s0, s0, s42
	s_lshl_b32 s0, s0, 13
	s_add_u32 s10, s4, s0
	s_addc_u32 s11, s5, 0
	global_load_dwordx4 v[28:31], v48, s[10:11]
	s_add_i32 s99, s40, 4
	s_add_i32 s0, s42, s99
	s_lshl_b32 s0, s0, 13
	s_add_u32 s8, s4, s0
	s_addc_u32 s9, s5, 0
	global_load_dwordx4 v[50:53], v48, s[8:9]
	s_add_u32 s8, s8, 0x2000
	s_addc_u32 s9, s9, 0
	global_load_dwordx4 v[54:57], v48, s[8:9]
	s_add_u32 s8, s8, 0x2000
	s_addc_u32 s9, s9, 0
	global_load_dwordx4 v[58:61], v48, s[8:9]
	s_add_u32 s8, s8, 0x2000
	s_addc_u32 s9, s9, 0
	global_load_dwordx4 v[62:65], v48, s[8:9]
	s_sub_i32 s1, s99, s43
	s_add_i32 s0, s1, 0
	s_max_i32 s0, s0, 0
	s_add_i32 s0, s0, s42
	s_lshl_b32 s0, s0, 13
	s_add_u32 s10, s4, s0
	s_addc_u32 s11, s5, 0
	global_load_dwordx4 v[66:69], v48, s[10:11]
	s_add_i32 s0, s1, 1
	s_max_i32 s0, s0, 0
	s_add_i32 s0, s0, s42
	s_lshl_b32 s0, s0, 13
	s_add_u32 s10, s4, s0
	s_addc_u32 s11, s5, 0
	global_load_dwordx4 v[70:73], v48, s[10:11]
	s_add_i32 s0, s1, 2
	s_max_i32 s0, s0, 0
	s_add_i32 s0, s0, s42
	s_lshl_b32 s0, s0, 13
	s_add_u32 s10, s4, s0
	s_addc_u32 s11, s5, 0
	global_load_dwordx4 v[74:77], v48, s[10:11]
	s_add_i32 s0, s1, 3
	s_max_i32 s0, s0, 0
	s_add_i32 s0, s0, s42
	s_lshl_b32 s0, s0, 13
	s_add_u32 s10, s4, s0
	s_addc_u32 s11, s5, 0
	global_load_dwordx4 v[78:81], v48, s[10:11]
	s_cmp_lg_u32 s41, 16
	s_cbranch_scc1 .Lpl_nox_1
	s_cmp_eq_u32 s98, 0
	s_cbranch_scc1 .Lpl_nox_1
	s_add_i32 s0, s42, s98
	s_lshl_b32 s0, s0, 13
	s_add_u32 s8, s4, s0
	s_addc_u32 s9, s5, 0
	s_sub_u32 s8, s8, 0x2000
	s_subb_u32 s9, s9, 0
	global_load_dwordx4 v[40:43], v48, s[8:9]
	s_sub_u32 s8, s8, 0x2000
	s_subb_u32 s9, s9, 0
	global_load_dwordx4 v[44:47], v48, s[8:9]
	s_sub_u32 s8, s8, 0x2000
	s_subb_u32 s9, s9, 0
	global_load_dwordx4 v[82:85], v48, s[8:9]
	s_sub_u32 s8, s8, 0x2000
	s_subb_u32 s9, s9, 0
	global_load_dwordx4 v[86:89], v48, s[8:9]
	s_sub_u32 s8, s8, 0x2000
	s_subb_u32 s9, s9, 0
	global_load_dwordx4 v[90:93], v48, s[8:9]
	s_sub_u32 s8, s8, 0x2000
	s_subb_u32 s9, s9, 0
	global_load_dwordx4 v[98:101], v48, s[8:9]
	s_sub_u32 s8, s8, 0x2000
	s_subb_u32 s9, s9, 0
	global_load_dwordx4 v[102:105], v48, s[8:9]
.Lpl_nox_1:
	s_waitcnt vmcnt(0)
	s_cmp_eq_u32 s98, 0
	s_cbranch_scc1 .Lpl_wdone_2
	s_cmp_eq_u32 s41, 4
	s_cbranch_scc1 .Lpl_w4_3
	s_cmp_eq_u32 s41, 8
	s_cbranch_scc1 .Lpl_w8_4
	s_cmp_eq_u32 s41, 16
	s_cbranch_scc1 .Lpl_w16_5
	v_lshlrev_b32_e32 v106, 16, v16
	v_and_b32_e32 v107, 0xffff0000, v16
	v_lshlrev_b32_e32 v108, 16, v17
	v_and_b32_e32 v109, 0xffff0000, v17
	v_lshlrev_b32_e32 v110, 16, v18
	v_and_b32_e32 v111, 0xffff0000, v18
	v_lshlrev_b32_e32 v112, 16, v19
	v_and_b32_e32 v113, 0xffff0000, v19
	v_pk_add_f32 v[32:33], v[32:33], v[106:107]
	v_pk_add_f32 v[34:35], v[34:35], v[108:109]
	v_pk_add_f32 v[36:37], v[36:37], v[110:111]
	v_pk_add_f32 v[38:39], v[38:39], v[112:113]
	s_branch .Lpl_wdone_2
.Lpl_w4_3:
	v_lshlrev_b32_e32 v106, 16, v24
	v_and_b32_e32 v107, 0xffff0000, v24
	v_lshlrev_b32_e32 v108, 16, v25
	v_and_b32_e32 v109, 0xffff0000, v25
	v_lshlrev_b32_e32 v110, 16, v26
	v_and_b32_e32 v111, 0xffff0000, v26
	v_lshlrev_b32_e32 v112, 16, v27
	v_and_b32_e32 v113, 0xffff0000, v27
	v_pk_add_f32 v[32:33], v[32:33], v[106:107]
	v_pk_add_f32 v[34:35], v[34:35], v[108:109]
	v_pk_add_f32 v[36:37], v[36:37], v[110:111]
	v_pk_add_f32 v[38:39], v[38:39], v[112:113]
	v_lshlrev_b32_e32 v106, 16, v20
	v_and_b32_e32 v107, 0xffff0000, v20
	v_lshlrev_b32_e32 v108, 16, v21
	v_and_b32_e32 v109, 0xffff0000, v21
	v_lshlrev_b32_e32 v110, 16, v22
	v_and_b32_e32 v111, 0xffff0000, v22
	v_lshlrev_b32_e32 v112, 16, v23
	v_and_b32_e32 v113, 0xffff0000, v23
	v_pk_add_f32 v[32:33], v[32:33], v[106:107]
	v_pk_add_f32 v[34:35], v[34:35], v[108:109]
	v_pk_add_f32 v[36:37], v[36:37], v[110:111]
	v_pk_add_f32 v[38:39], v[38:39], v[112:113]
	v_lshlrev_b32_e32 v106, 16, v16
	v_and_b32_e32 v107, 0xffff0000, v16
	v_lshlrev_b32_e32 v108, 16, v17
	v_and_b32_e32 v109, 0xffff0000, v17
	v_lshlrev_b32_e32 v110, 16, v18
	v_and_b32_e32 v111, 0xffff0000, v18
	v_lshlrev_b32_e32 v112, 16, v19
	v_and_b32_e32 v113, 0xffff0000, v19
	v_pk_add_f32 v[32:33], v[32:33], v[106:107]
	v_pk_add_f32 v[34:35], v[34:35], v[108:109]
	v_pk_add_f32 v[36:37], v[36:37], v[110:111]
	v_pk_add_f32 v[38:39], v[38:39], v[112:113]
	s_branch .Lpl_wdone_2
.Lpl_w8_4:
	v_lshlrev_b32_e32 v106, 16, v74
	v_and_b32_e32 v107, 0xffff0000, v74
	v_lshlrev_b32_e32 v108, 16, v75
	v_and_b32_e32 v109, 0xffff0000, v75
	v_lshlrev_b32_e32 v110, 16, v76
	v_and_b32_e32 v111, 0xffff0000, v76
	v_lshlrev_b32_e32 v112, 16, v77
	v_and_b32_e32 v113, 0xffff0000, v77
	v_pk_add_f32 v[32:33], v[32:33], v[106:107]
	v_pk_add_f32 v[34:35], v[34:35], v[108:109]
	v_pk_add_f32 v[36:37], v[36:37], v[110:111]
	v_pk_add_f32 v[38:39], v[38:39], v[112:113]
	v_lshlrev_b32_e32 v106, 16, v70
	v_and_b32_e32 v107, 0xffff0000, v70
	v_lshlrev_b32_e32 v108, 16, v71
	v_and_b32_e32 v109, 0xffff0000, v71
	v_lshlrev_b32_e32 v110, 16, v72
	v_and_b32_e32 v111, 0xffff0000, v72
	v_lshlrev_b32_e32 v112, 16, v73
	v_and_b32_e32 v113, 0xffff0000, v73
	v_pk_add_f32 v[32:33], v[32:33], v[106:107]
	v_pk_add_f32 v[34:35], v[34:35], v[108:109]
	v_pk_add_f32 v[36:37], v[36:37], v[110:111]
	v_pk_add_f32 v[38:39], v[38:39], v[112:113]
	v_lshlrev_b32_e32 v106, 16, v66
	v_and_b32_e32 v107, 0xffff0000, v66
	v_lshlrev_b32_e32 v108, 16, v67
	v_and_b32_e32 v109, 0xffff0000, v67
	v_lshlrev_b32_e32 v110, 16, v68
	v_and_b32_e32 v111, 0xffff0000, v68
	v_lshlrev_b32_e32 v112, 16, v69
	v_and_b32_e32 v113, 0xffff0000, v69
	v_pk_add_f32 v[32:33], v[32:33], v[106:107]
	v_pk_add_f32 v[34:35], v[34:35], v[108:109]
	v_pk_add_f32 v[36:37], v[36:37], v[110:111]
	v_pk_add_f32 v[38:39], v[38:39], v[112:113]
	v_lshlrev_b32_e32 v106, 16, v28
	v_and_b32_e32 v107, 0xffff0000, v28
	v_lshlrev_b32_e32 v108, 16, v29
	v_and_b32_e32 v109, 0xffff0000, v29
	v_lshlrev_b32_e32 v110, 16, v30
	v_and_b32_e32 v111, 0xffff0000, v30
	v_lshlrev_b32_e32 v112, 16, v31
	v_and_b32_e32 v113, 0xffff0000, v31
	v_pk_add_f32 v[32:33], v[32:33], v[106:107]
	v_pk_add_f32 v[34:35], v[34:35], v[108:109]
	v_pk_add_f32 v[36:37], v[36:37], v[110:111]
	v_pk_add_f32 v[38:39], v[38:39], v[112:113]
	v_lshlrev_b32_e32 v106, 16, v24
	v_and_b32_e32 v107, 0xffff0000, v24
	v_lshlrev_b32_e32 v108, 16, v25
	v_and_b32_e32 v109, 0xffff0000, v25
	v_lshlrev_b32_e32 v110, 16, v26
	v_and_b32_e32 v111, 0xffff0000, v26
	v_lshlrev_b32_e32 v112, 16, v27
	v_and_b32_e32 v113, 0xffff0000, v27
	v_pk_add_f32 v[32:33], v[32:33], v[106:107]
	v_pk_add_f32 v[34:35], v[34:35], v[108:109]
	v_pk_add_f32 v[36:37], v[36:37], v[110:111]
	v_pk_add_f32 v[38:39], v[38:39], v[112:113]
	v_lshlrev_b32_e32 v106, 16, v20
	v_and_b32_e32 v107, 0xffff0000, v20
	v_lshlrev_b32_e32 v108, 16, v21
	v_and_b32_e32 v109, 0xffff0000, v21
	v_lshlrev_b32_e32 v110, 16, v22
	v_and_b32_e32 v111, 0xffff0000, v22
	v_lshlrev_b32_e32 v112, 16, v23
	v_and_b32_e32 v113, 0xffff0000, v23
	v_pk_add_f32 v[32:33], v[32:33], v[106:107]
	v_pk_add_f32 v[34:35], v[34:35], v[108:109]
	v_pk_add_f32 v[36:37], v[36:37], v[110:111]
	v_pk_add_f32 v[38:39], v[38:39], v[112:113]
	v_lshlrev_b32_e32 v106, 16, v16
	v_and_b32_e32 v107, 0xffff0000, v16
	v_lshlrev_b32_e32 v108, 16, v17
	v_and_b32_e32 v109, 0xffff0000, v17
	v_lshlrev_b32_e32 v110, 16, v18
	v_and_b32_e32 v111, 0xffff0000, v18
	v_lshlrev_b32_e32 v112, 16, v19
	v_and_b32_e32 v113, 0xffff0000, v19
	v_pk_add_f32 v[32:33], v[32:33], v[106:107]
	v_pk_add_f32 v[34:35], v[34:35], v[108:109]
	v_pk_add_f32 v[36:37], v[36:37], v[110:111]
	v_pk_add_f32 v[38:39], v[38:39], v[112:113]
	s_branch .Lpl_wdone_2
.Lpl_w16_5:
	v_lshlrev_b32_e32 v106, 16, v40
	v_and_b32_e32 v107, 0xffff0000, v40
	v_lshlrev_b32_e32 v108, 16, v41
	v_and_b32_e32 v109, 0xffff0000, v41
	v_lshlrev_b32_e32 v110, 16, v42
	v_and_b32_e32 v111, 0xffff0000, v42
	v_lshlrev_b32_e32 v112, 16, v43
	v_and_b32_e32 v113, 0xffff0000, v43
	v_pk_add_f32 v[32:33], v[32:33], v[106:107]
	v_pk_add_f32 v[34:35], v[34:35], v[108:109]
	v_pk_add_f32 v[36:37], v[36:37], v[110:111]
	v_pk_add_f32 v[38:39], v[38:39], v[112:113]
	v_lshlrev_b32_e32 v106, 16, v44
	v_and_b32_e32 v107, 0xffff0000, v44
	v_lshlrev_b32_e32 v108, 16, v45
	v_and_b32_e32 v109, 0xffff0000, v45
	v_lshlrev_b32_e32 v110, 16, v46
	v_and_b32_e32 v111, 0xffff0000, v46
	v_lshlrev_b32_e32 v112, 16, v47
	v_and_b32_e32 v113, 0xffff0000, v47
	v_pk_add_f32 v[32:33], v[32:33], v[106:107]
	v_pk_add_f32 v[34:35], v[34:35], v[108:109]
	v_pk_add_f32 v[36:37], v[36:37], v[110:111]
	v_pk_add_f32 v[38:39], v[38:39], v[112:113]
	v_lshlrev_b32_e32 v106, 16, v82
	v_and_b32_e32 v107, 0xffff0000, v82
	v_lshlrev_b32_e32 v108, 16, v83
	v_and_b32_e32 v109, 0xffff0000, v83
	v_lshlrev_b32_e32 v110, 16, v84
	v_and_b32_e32 v111, 0xffff0000, v84
	v_lshlrev_b32_e32 v112, 16, v85
	v_and_b32_e32 v113, 0xffff0000, v85
	v_pk_add_f32 v[32:33], v[32:33], v[106:107]
	v_pk_add_f32 v[34:35], v[34:35], v[108:109]
	v_pk_add_f32 v[36:37], v[36:37], v[110:111]
	v_pk_add_f32 v[38:39], v[38:39], v[112:113]
	v_lshlrev_b32_e32 v106, 16, v86
	v_and_b32_e32 v107, 0xffff0000, v86
	v_lshlrev_b32_e32 v108, 16, v87
	v_and_b32_e32 v109, 0xffff0000, v87
	v_lshlrev_b32_e32 v110, 16, v88
	v_and_b32_e32 v111, 0xffff0000, v88
	v_lshlrev_b32_e32 v112, 16, v89
	v_and_b32_e32 v113, 0xffff0000, v89
	v_pk_add_f32 v[32:33], v[32:33], v[106:107]
	v_pk_add_f32 v[34:35], v[34:35], v[108:109]
	v_pk_add_f32 v[36:37], v[36:37], v[110:111]
	v_pk_add_f32 v[38:39], v[38:39], v[112:113]
	v_lshlrev_b32_e32 v106, 16, v90
	v_and_b32_e32 v107, 0xffff0000, v90
	v_lshlrev_b32_e32 v108, 16, v91
	v_and_b32_e32 v109, 0xffff0000, v91
	v_lshlrev_b32_e32 v110, 16, v92
	v_and_b32_e32 v111, 0xffff0000, v92
	v_lshlrev_b32_e32 v112, 16, v93
	v_and_b32_e32 v113, 0xffff0000, v93
	v_pk_add_f32 v[32:33], v[32:33], v[106:107]
	v_pk_add_f32 v[34:35], v[34:35], v[108:109]
	v_pk_add_f32 v[36:37], v[36:37], v[110:111]
	v_pk_add_f32 v[38:39], v[38:39], v[112:113]
	v_lshlrev_b32_e32 v106, 16, v98
	v_and_b32_e32 v107, 0xffff0000, v98
	v_lshlrev_b32_e32 v108, 16, v99
	v_and_b32_e32 v109, 0xffff0000, v99
	v_lshlrev_b32_e32 v110, 16, v100
	v_and_b32_e32 v111, 0xffff0000, v100
	v_lshlrev_b32_e32 v112, 16, v101
	v_and_b32_e32 v113, 0xffff0000, v101
	v_pk_add_f32 v[32:33], v[32:33], v[106:107]
	v_pk_add_f32 v[34:35], v[34:35], v[108:109]
	v_pk_add_f32 v[36:37], v[36:37], v[110:111]
	v_pk_add_f32 v[38:39], v[38:39], v[112:113]
	v_lshlrev_b32_e32 v106, 16, v102
	v_and_b32_e32 v107, 0xffff0000, v102
	v_lshlrev_b32_e32 v108, 16, v103
	v_and_b32_e32 v109, 0xffff0000, v103
	v_lshlrev_b32_e32 v110, 16, v104
	v_and_b32_e32 v111, 0xffff0000, v104
	v_lshlrev_b32_e32 v112, 16, v105
	v_and_b32_e32 v113, 0xffff0000, v105
	v_pk_add_f32 v[32:33], v[32:33], v[106:107]
	v_pk_add_f32 v[34:35], v[34:35], v[108:109]
	v_pk_add_f32 v[36:37], v[36:37], v[110:111]
	v_pk_add_f32 v[38:39], v[38:39], v[112:113]
	v_lshlrev_b32_e32 v106, 16, v78
	v_and_b32_e32 v107, 0xffff0000, v78
	v_lshlrev_b32_e32 v108, 16, v79
	v_and_b32_e32 v109, 0xffff0000, v79
	v_lshlrev_b32_e32 v110, 16, v80
	v_and_b32_e32 v111, 0xffff0000, v80
	v_lshlrev_b32_e32 v112, 16, v81
	v_and_b32_e32 v113, 0xffff0000, v81
	v_pk_add_f32 v[32:33], v[32:33], v[106:107]
	v_pk_add_f32 v[34:35], v[34:35], v[108:109]
	v_pk_add_f32 v[36:37], v[36:37], v[110:111]
	v_pk_add_f32 v[38:39], v[38:39], v[112:113]
	v_lshlrev_b32_e32 v106, 16, v74
	v_and_b32_e32 v107, 0xffff0000, v74
	v_lshlrev_b32_e32 v108, 16, v75
	v_and_b32_e32 v109, 0xffff0000, v75
	v_lshlrev_b32_e32 v110, 16, v76
	v_and_b32_e32 v111, 0xffff0000, v76
	v_lshlrev_b32_e32 v112, 16, v77
	v_and_b32_e32 v113, 0xffff0000, v77
	v_pk_add_f32 v[32:33], v[32:33], v[106:107]
	v_pk_add_f32 v[34:35], v[34:35], v[108:109]
	v_pk_add_f32 v[36:37], v[36:37], v[110:111]
	v_pk_add_f32 v[38:39], v[38:39], v[112:113]
	v_lshlrev_b32_e32 v106, 16, v70
	v_and_b32_e32 v107, 0xffff0000, v70
	v_lshlrev_b32_e32 v108, 16, v71
	v_and_b32_e32 v109, 0xffff0000, v71
	v_lshlrev_b32_e32 v110, 16, v72
	v_and_b32_e32 v111, 0xffff0000, v72
	v_lshlrev_b32_e32 v112, 16, v73
	v_and_b32_e32 v113, 0xffff0000, v73
	v_pk_add_f32 v[32:33], v[32:33], v[106:107]
	v_pk_add_f32 v[34:35], v[34:35], v[108:109]
	v_pk_add_f32 v[36:37], v[36:37], v[110:111]
	v_pk_add_f32 v[38:39], v[38:39], v[112:113]
	v_lshlrev_b32_e32 v106, 16, v66
	v_and_b32_e32 v107, 0xffff0000, v66
	v_lshlrev_b32_e32 v108, 16, v67
	v_and_b32_e32 v109, 0xffff0000, v67
	v_lshlrev_b32_e32 v110, 16, v68
	v_and_b32_e32 v111, 0xffff0000, v68
	v_lshlrev_b32_e32 v112, 16, v69
	v_and_b32_e32 v113, 0xffff0000, v69
	v_pk_add_f32 v[32:33], v[32:33], v[106:107]
	v_pk_add_f32 v[34:35], v[34:35], v[108:109]
	v_pk_add_f32 v[36:37], v[36:37], v[110:111]
	v_pk_add_f32 v[38:39], v[38:39], v[112:113]
	v_lshlrev_b32_e32 v106, 16, v28
	v_and_b32_e32 v107, 0xffff0000, v28
	v_lshlrev_b32_e32 v108, 16, v29
	v_and_b32_e32 v109, 0xffff0000, v29
	v_lshlrev_b32_e32 v110, 16, v30
	v_and_b32_e32 v111, 0xffff0000, v30
	v_lshlrev_b32_e32 v112, 16, v31
	v_and_b32_e32 v113, 0xffff0000, v31
	v_pk_add_f32 v[32:33], v[32:33], v[106:107]
	v_pk_add_f32 v[34:35], v[34:35], v[108:109]
	v_pk_add_f32 v[36:37], v[36:37], v[110:111]
	v_pk_add_f32 v[38:39], v[38:39], v[112:113]
	v_lshlrev_b32_e32 v106, 16, v24
	v_and_b32_e32 v107, 0xffff0000, v24
	v_lshlrev_b32_e32 v108, 16, v25
	v_and_b32_e32 v109, 0xffff0000, v25
	v_lshlrev_b32_e32 v110, 16, v26
	v_and_b32_e32 v111, 0xffff0000, v26
	v_lshlrev_b32_e32 v112, 16, v27
	v_and_b32_e32 v113, 0xffff0000, v27
	v_pk_add_f32 v[32:33], v[32:33], v[106:107]
	v_pk_add_f32 v[34:35], v[34:35], v[108:109]
	v_pk_add_f32 v[36:37], v[36:37], v[110:111]
	v_pk_add_f32 v[38:39], v[38:39], v[112:113]
	v_lshlrev_b32_e32 v106, 16, v20
	v_and_b32_e32 v107, 0xffff0000, v20
	v_lshlrev_b32_e32 v108, 16, v21
	v_and_b32_e32 v109, 0xffff0000, v21
	v_lshlrev_b32_e32 v110, 16, v22
	v_and_b32_e32 v111, 0xffff0000, v22
	v_lshlrev_b32_e32 v112, 16, v23
	v_and_b32_e32 v113, 0xffff0000, v23
	v_pk_add_f32 v[32:33], v[32:33], v[106:107]
	v_pk_add_f32 v[34:35], v[34:35], v[108:109]
	v_pk_add_f32 v[36:37], v[36:37], v[110:111]
	v_pk_add_f32 v[38:39], v[38:39], v[112:113]
	v_lshlrev_b32_e32 v106, 16, v16
	v_and_b32_e32 v107, 0xffff0000, v16
	v_lshlrev_b32_e32 v108, 16, v17
	v_and_b32_e32 v109, 0xffff0000, v17
	v_lshlrev_b32_e32 v110, 16, v18
	v_and_b32_e32 v111, 0xffff0000, v18
	v_lshlrev_b32_e32 v112, 16, v19
	v_and_b32_e32 v113, 0xffff0000, v19
	v_pk_add_f32 v[32:33], v[32:33], v[106:107]
	v_pk_add_f32 v[34:35], v[34:35], v[108:109]
	v_pk_add_f32 v[36:37], v[36:37], v[110:111]
	v_pk_add_f32 v[38:39], v[38:39], v[112:113]
.Lpl_wdone_2:
.Lpl_loop_6:
	s_add_i32 s0, s40, 1
	s_min_i32 s0, s0, s41
	v_cvt_f32_u32_e32 v98, s0
	v_div_scale_f32 v99, s[100:101], v98, v98, 1.0
	v_rcp_f32_e32 v100, v99
	s_nop 0
	v_fma_f32 v101, -v99, v100, 1.0
	v_fmac_f32_e32 v100, v101, v100
	v_div_scale_f32 v101, vcc, 1.0, v98, 1.0
	v_mul_f32_e32 v102, v101, v100
	v_fma_f32 v103, -v99, v102, v101
	v_fmac_f32_e32 v102, v103, v100
	v_fma_f32 v99, -v99, v102, v101
	v_div_fmas_f32 v99, v99, v100, v102
	v_div_fixup_f32 v94, v99, v98, 1.0
	v_mov_b32_e32 v95, v94
	v_lshlrev_b32_e32 v40, 16, v0
	v_and_b32_e32 v41, 0xffff0000, v0
	v_lshlrev_b32_e32 v42, 16, v1
	v_and_b32_e32 v43, 0xffff0000, v1
	v_lshlrev_b32_e32 v44, 16, v2
	v_and_b32_e32 v45, 0xffff0000, v2
	v_lshlrev_b32_e32 v46, 16, v3
	v_and_b32_e32 v47, 0xffff0000, v3
	v_pk_add_f32 v[32:33], v[32:33], v[40:41]
	v_pk_add_f32 v[34:35], v[34:35], v[42:43]
	v_pk_add_f32 v[36:37], v[36:37], v[44:45]
	v_pk_add_f32 v[38:39], v[38:39], v[46:47]
	v_pk_fma_f32 v[82:83], v[32:33], v[94:95], v[40:41] neg_lo:[0,0,1] neg_hi:[0,0,1]
	v_pk_fma_f32 v[84:85], v[34:35], v[94:95], v[42:43] neg_lo:[0,0,1] neg_hi:[0,0,1]
	v_pk_fma_f32 v[86:87], v[36:37], v[94:95], v[44:45] neg_lo:[0,0,1] neg_hi:[0,0,1]
	v_pk_fma_f32 v[88:89], v[38:39], v[94:95], v[46:47] neg_lo:[0,0,1] neg_hi:[0,0,1]
	v_cvt_pk_bf16_f32 v90, v82, v83
	v_cvt_pk_bf16_f32 v91, v84, v85
	v_cvt_pk_bf16_f32 v92, v86, v87
	v_cvt_pk_bf16_f32 v93, v88, v89
	global_store_dwordx4 v48, v[90:93], s[22:23]
	s_add_u32 s22, s22, 0x1000
	s_addc_u32 s23, s23, 0
	s_add_i32 s0, s40, 0
	s_cmp_lt_i32 s0, s43
	s_cbranch_scc1 .Lpl_sk_7
	v_lshlrev_b32_e32 v82, 16, v16
	v_and_b32_e32 v83, 0xffff0000, v16
	v_lshlrev_b32_e32 v84, 16, v17
	v_and_b32_e32 v85, 0xffff0000, v17
	v_lshlrev_b32_e32 v86, 16, v18
	v_and_b32_e32 v87, 0xffff0000, v18
	v_lshlrev_b32_e32 v88, 16, v19
	v_and_b32_e32 v89, 0xffff0000, v19
	v_pk_add_f32 v[32:33], v[32:33], v[82:83] neg_lo:[0,1] neg_hi:[0,1]
	v_pk_add_f32 v[34:35], v[34:35], v[84:85] neg_lo:[0,1] neg_hi:[0,1]
	v_pk_add_f32 v[36:37], v[36:37], v[86:87] neg_lo:[0,1] neg_hi:[0,1]
	v_pk_add_f32 v[38:39], v[38:39], v[88:89] neg_lo:[0,1] neg_hi:[0,1]
.Lpl_sk_7:
	s_add_i32 s0, s40, 2
	s_min_i32 s0, s0, s41
	v_cvt_f32_u32_e32 v98, s0
	v_div_scale_f32 v99, s[100:101], v98, v98, 1.0
	v_rcp_f32_e32 v100, v99
	s_nop 0
	v_fma_f32 v101, -v99, v100, 1.0
	v_fmac_f32_e32 v100, v101, v100
	v_div_scale_f32 v101, vcc, 1.0, v98, 1.0
	v_mul_f32_e32 v102, v101, v100
	v_fma_f32 v103, -v99, v102, v101
	v_fmac_f32_e32 v102, v103, v100
	v_fma_f32 v99, -v99, v102, v101
	v_div_fmas_f32 v99, v99, v100, v102
	v_div_fixup_f32 v94, v99, v98, 1.0
	v_mov_b32_e32 v95, v94
	v_lshlrev_b32_e32 v40, 16, v4
	v_and_b32_e32 v41, 0xffff0000, v4
	v_lshlrev_b32_e32 v42, 16, v5
	v_and_b32_e32 v43, 0xffff0000, v5
	v_lshlrev_b32_e32 v44, 16, v6
	v_and_b32_e32 v45, 0xffff0000, v6
	v_lshlrev_b32_e32 v46, 16, v7
	v_and_b32_e32 v47, 0xffff0000, v7
	v_pk_add_f32 v[32:33], v[32:33], v[40:41]
	v_pk_add_f32 v[34:35], v[34:35], v[42:43]
	v_pk_add_f32 v[36:37], v[36:37], v[44:45]
	v_pk_add_f32 v[38:39], v[38:39], v[46:47]
	v_pk_fma_f32 v[82:83], v[32:33], v[94:95], v[40:41] neg_lo:[0,0,1] neg_hi:[0,0,1]
	v_pk_fma_f32 v[84:85], v[34:35], v[94:95], v[42:43] neg_lo:[0,0,1] neg_hi:[0,0,1]
	v_pk_fma_f32 v[86:87], v[36:37], v[94:95], v[44:45] neg_lo:[0,0,1] neg_hi:[0,0,1]
	v_pk_fma_f32 v[88:89], v[38:39], v[94:95], v[46:47] neg_lo:[0,0,1] neg_hi:[0,0,1]
	v_cvt_pk_bf16_f32 v90, v82, v83
	v_cvt_pk_bf16_f32 v91, v84, v85
	v_cvt_pk_bf16_f32 v92, v86, v87
	v_cvt_pk_bf16_f32 v93, v88, v89
	global_store_dwordx4 v48, v[90:93], s[22:23]
	s_add_u32 s22, s22, 0x1000
	s_addc_u32 s23, s23, 0
	s_add_i32 s0, s40, 1
	s_cmp_lt_i32 s0, s43
	s_cbranch_scc1 .Lpl_sk_8
	v_lshlrev_b32_e32 v82, 16, v20
	v_and_b32_e32 v83, 0xffff0000, v20
	v_lshlrev_b32_e32 v84, 16, v21
	v_and_b32_e32 v85, 0xffff0000, v21
	v_lshlrev_b32_e32 v86, 16, v22
	v_and_b32_e32 v87, 0xffff0000, v22
	v_lshlrev_b32_e32 v88, 16, v23
	v_and_b32_e32 v89, 0xffff0000, v23
	v_pk_add_f32 v[32:33], v[32:33], v[82:83] neg_lo:[0,1] neg_hi:[0,1]
	v_pk_add_f32 v[34:35], v[34:35], v[84:85] neg_lo:[0,1] neg_hi:[0,1]
	v_pk_add_f32 v[36:37], v[36:37], v[86:87] neg_lo:[0,1] neg_hi:[0,1]
	v_pk_add_f32 v[38:39], v[38:39], v[88:89] neg_lo:[0,1] neg_hi:[0,1]
.Lpl_sk_8:
	s_add_i32 s0, s40, 3
	s_min_i32 s0, s0, s41
	v_cvt_f32_u32_e32 v98, s0
	v_div_scale_f32 v99, s[100:101], v98, v98, 1.0
	v_rcp_f32_e32 v100, v99
	s_nop 0
	v_fma_f32 v101, -v99, v100, 1.0
	v_fmac_f32_e32 v100, v101, v100
	v_div_scale_f32 v101, vcc, 1.0, v98, 1.0
	v_mul_f32_e32 v102, v101, v100
	v_fma_f32 v103, -v99, v102, v101
	v_fmac_f32_e32 v102, v103, v100
	v_fma_f32 v99, -v99, v102, v101
	v_div_fmas_f32 v99, v99, v100, v102
	v_div_fixup_f32 v94, v99, v98, 1.0
	v_mov_b32_e32 v95, v94
	v_lshlrev_b32_e32 v40, 16, v8
	v_and_b32_e32 v41, 0xffff0000, v8
	v_lshlrev_b32_e32 v42, 16, v9
	v_and_b32_e32 v43, 0xffff0000, v9
	v_lshlrev_b32_e32 v44, 16, v10
	v_and_b32_e32 v45, 0xffff0000, v10
	v_lshlrev_b32_e32 v46, 16, v11
	v_and_b32_e32 v47, 0xffff0000, v11
	v_pk_add_f32 v[32:33], v[32:33], v[40:41]
	v_pk_add_f32 v[34:35], v[34:35], v[42:43]
	v_pk_add_f32 v[36:37], v[36:37], v[44:45]
	v_pk_add_f32 v[38:39], v[38:39], v[46:47]
	v_pk_fma_f32 v[82:83], v[32:33], v[94:95], v[40:41] neg_lo:[0,0,1] neg_hi:[0,0,1]
	v_pk_fma_f32 v[84:85], v[34:35], v[94:95], v[42:43] neg_lo:[0,0,1] neg_hi:[0,0,1]
	v_pk_fma_f32 v[86:87], v[36:37], v[94:95], v[44:45] neg_lo:[0,0,1] neg_hi:[0,0,1]
	v_pk_fma_f32 v[88:89], v[38:39], v[94:95], v[46:47] neg_lo:[0,0,1] neg_hi:[0,0,1]
	v_cvt_pk_bf16_f32 v90, v82, v83
	v_cvt_pk_bf16_f32 v91, v84, v85
	v_cvt_pk_bf16_f32 v92, v86, v87
	v_cvt_pk_bf16_f32 v93, v88, v89
	global_store_dwordx4 v48, v[90:93], s[22:23]
	s_add_u32 s22, s22, 0x1000
	s_addc_u32 s23, s23, 0
	s_add_i32 s0, s40, 2
	s_cmp_lt_i32 s0, s43
	s_cbranch_scc1 .Lpl_sk_9
	v_lshlrev_b32_e32 v82, 16, v24
	v_and_b32_e32 v83, 0xffff0000, v24
	v_lshlrev_b32_e32 v84, 16, v25
	v_and_b32_e32 v85, 0xffff0000, v25
	v_lshlrev_b32_e32 v86, 16, v26
	v_and_b32_e32 v87, 0xffff0000, v26
	v_lshlrev_b32_e32 v88, 16, v27
	v_and_b32_e32 v89, 0xffff0000, v27
	v_pk_add_f32 v[32:33], v[32:33], v[82:83] neg_lo:[0,1] neg_hi:[0,1]
	v_pk_add_f32 v[34:35], v[34:35], v[84:85] neg_lo:[0,1] neg_hi:[0,1]
	v_pk_add_f32 v[36:37], v[36:37], v[86:87] neg_lo:[0,1] neg_hi:[0,1]
	v_pk_add_f32 v[38:39], v[38:39], v[88:89] neg_lo:[0,1] neg_hi:[0,1]
.Lpl_sk_9:
	s_add_i32 s0, s40, 4
	s_min_i32 s0, s0, s41
	v_cvt_f32_u32_e32 v98, s0
	v_div_scale_f32 v99, s[100:101], v98, v98, 1.0
	v_rcp_f32_e32 v100, v99
	s_nop 0
	v_fma_f32 v101, -v99, v100, 1.0
	v_fmac_f32_e32 v100, v101, v100
	v_div_scale_f32 v101, vcc, 1.0, v98, 1.0
	v_mul_f32_e32 v102, v101, v100
	v_fma_f32 v103, -v99, v102, v101
	v_fmac_f32_e32 v102, v103, v100
	v_fma_f32 v99, -v99, v102, v101
	v_div_fmas_f32 v99, v99, v100, v102
	v_div_fixup_f32 v94, v99, v98, 1.0
	v_mov_b32_e32 v95, v94
	v_lshlrev_b32_e32 v40, 16, v12
	v_and_b32_e32 v41, 0xffff0000, v12
	v_lshlrev_b32_e32 v42, 16, v13
	v_and_b32_e32 v43, 0xffff0000, v13
	v_lshlrev_b32_e32 v44, 16, v14
	v_and_b32_e32 v45, 0xffff0000, v14
	v_lshlrev_b32_e32 v46, 16, v15
	v_and_b32_e32 v47, 0xffff0000, v15
	v_pk_add_f32 v[32:33], v[32:33], v[40:41]
	v_pk_add_f32 v[34:35], v[34:35], v[42:43]
	v_pk_add_f32 v[36:37], v[36:37], v[44:45]
	v_pk_add_f32 v[38:39], v[38:39], v[46:47]
	v_pk_fma_f32 v[82:83], v[32:33], v[94:95], v[40:41] neg_lo:[0,0,1] neg_hi:[0,0,1]
	v_pk_fma_f32 v[84:85], v[34:35], v[94:95], v[42:43] neg_lo:[0,0,1] neg_hi:[0,0,1]
	v_pk_fma_f32 v[86:87], v[36:37], v[94:95], v[44:45] neg_lo:[0,0,1] neg_hi:[0,0,1]
	v_pk_fma_f32 v[88:89], v[38:39], v[94:95], v[46:47] neg_lo:[0,0,1] neg_hi:[0,0,1]
	v_cvt_pk_bf16_f32 v90, v82, v83
	v_cvt_pk_bf16_f32 v91, v84, v85
	v_cvt_pk_bf16_f32 v92, v86, v87
	v_cvt_pk_bf16_f32 v93, v88, v89
	global_store_dwordx4 v48, v[90:93], s[22:23]
	s_add_u32 s22, s22, 0x1000
	s_addc_u32 s23, s23, 0
	s_add_i32 s0, s40, 3
	s_cmp_lt_i32 s0, s43
	s_cbranch_scc1 .Lpl_sk_10
	v_lshlrev_b32_e32 v82, 16, v28
	v_and_b32_e32 v83, 0xffff0000, v28
	v_lshlrev_b32_e32 v84, 16, v29
	v_and_b32_e32 v85, 0xffff0000, v29
	v_lshlrev_b32_e32 v86, 16, v30
	v_and_b32_e32 v87, 0xffff0000, v30
	v_lshlrev_b32_e32 v88, 16, v31
	v_and_b32_e32 v89, 0xffff0000, v31
	v_pk_add_f32 v[32:33], v[32:33], v[82:83] neg_lo:[0,1] neg_hi:[0,1]
	v_pk_add_f32 v[34:35], v[34:35], v[84:85] neg_lo:[0,1] neg_hi:[0,1]
	v_pk_add_f32 v[36:37], v[36:37], v[86:87] neg_lo:[0,1] neg_hi:[0,1]
	v_pk_add_f32 v[38:39], v[38:39], v[88:89] neg_lo:[0,1] neg_hi:[0,1]
.Lpl_sk_10:
	s_add_i32 s46, s40, 8
	s_add_i32 s0, s48, -4
	s_min_i32 s46, s46, s0
	s_add_i32 s0, s42, s46
	s_lshl_b32 s0, s0, 13
	s_add_u32 s8, s4, s0
	s_addc_u32 s9, s5, 0
	global_load_dwordx4 v[0:3], v48, s[8:9]
	s_add_u32 s8, s8, 0x2000
	s_addc_u32 s9, s9, 0
	global_load_dwordx4 v[4:7], v48, s[8:9]
	s_add_u32 s8, s8, 0x2000
	s_addc_u32 s9, s9, 0
	global_load_dwordx4 v[8:11], v48, s[8:9]
	s_add_u32 s8, s8, 0x2000
	s_addc_u32 s9, s9, 0
	global_load_dwordx4 v[12:15], v48, s[8:9]
	s_sub_i32 s1, s46, s43
	s_add_i32 s0, s1, 0
	s_max_i32 s0, s0, 0
	s_add_i32 s0, s0, s42
	s_lshl_b32 s0, s0, 13
	s_add_u32 s10, s4, s0
	s_addc_u32 s11, s5, 0
	global_load_dwordx4 v[16:19], v48, s[10:11]
	s_add_i32 s0, s1, 1
	s_max_i32 s0, s0, 0
	s_add_i32 s0, s0, s42
	s_lshl_b32 s0, s0, 13
	s_add_u32 s10, s4, s0
	s_addc_u32 s11, s5, 0
	global_load_dwordx4 v[20:23], v48, s[10:11]
	s_add_i32 s0, s1, 2
	s_max_i32 s0, s0, 0
	s_add_i32 s0, s0, s42
	s_lshl_b32 s0, s0, 13
	s_add_u32 s10, s4, s0
	s_addc_u32 s11, s5, 0
	global_load_dwordx4 v[24:27], v48, s[10:11]
	s_add_i32 s0, s1, 3
	s_max_i32 s0, s0, 0
	s_add_i32 s0, s0, s42
	s_lshl_b32 s0, s0, 13
	s_add_u32 s10, s4, s0
	s_addc_u32 s11, s5, 0
	global_load_dwordx4 v[28:31], v48, s[10:11]
	s_waitcnt vmcnt(12)
	s_add_i32 s99, s40, 4
	s_add_i32 s0, s99, 1
	s_min_i32 s0, s0, s41
	v_cvt_f32_u32_e32 v98, s0
	v_div_scale_f32 v99, s[100:101], v98, v98, 1.0
	v_rcp_f32_e32 v100, v99
	s_nop 0
	v_fma_f32 v101, -v99, v100, 1.0
	v_fmac_f32_e32 v100, v101, v100
	v_div_scale_f32 v101, vcc, 1.0, v98, 1.0
	v_mul_f32_e32 v102, v101, v100
	v_fma_f32 v103, -v99, v102, v101
	v_fmac_f32_e32 v102, v103, v100
	v_fma_f32 v99, -v99, v102, v101
	v_div_fmas_f32 v99, v99, v100, v102
	v_div_fixup_f32 v94, v99, v98, 1.0
	v_mov_b32_e32 v95, v94
	v_lshlrev_b32_e32 v40, 16, v50
	v_and_b32_e32 v41, 0xffff0000, v50
	v_lshlrev_b32_e32 v42, 16, v51
	v_and_b32_e32 v43, 0xffff0000, v51
	v_lshlrev_b32_e32 v44, 16, v52
	v_and_b32_e32 v45, 0xffff0000, v52
	v_lshlrev_b32_e32 v46, 16, v53
	v_and_b32_e32 v47, 0xffff0000, v53
	v_pk_add_f32 v[32:33], v[32:33], v[40:41]
	v_pk_add_f32 v[34:35], v[34:35], v[42:43]
	v_pk_add_f32 v[36:37], v[36:37], v[44:45]
	v_pk_add_f32 v[38:39], v[38:39], v[46:47]
	v_pk_fma_f32 v[82:83], v[32:33], v[94:95], v[40:41] neg_lo:[0,0,1] neg_hi:[0,0,1]
	v_pk_fma_f32 v[84:85], v[34:35], v[94:95], v[42:43] neg_lo:[0,0,1] neg_hi:[0,0,1]
	v_pk_fma_f32 v[86:87], v[36:37], v[94:95], v[44:45] neg_lo:[0,0,1] neg_hi:[0,0,1]
	v_pk_fma_f32 v[88:89], v[38:39], v[94:95], v[46:47] neg_lo:[0,0,1] neg_hi:[0,0,1]
	v_cvt_pk_bf16_f32 v90, v82, v83
	v_cvt_pk_bf16_f32 v91, v84, v85
	v_cvt_pk_bf16_f32 v92, v86, v87
	v_cvt_pk_bf16_f32 v93, v88, v89
	global_store_dwordx4 v48, v[90:93], s[22:23]
	s_add_u32 s22, s22, 0x1000
	s_addc_u32 s23, s23, 0
	s_add_i32 s0, s99, 0
	s_cmp_lt_i32 s0, s43
	s_cbranch_scc1 .Lpl_sk_11
	v_lshlrev_b32_e32 v82, 16, v66
	v_and_b32_e32 v83, 0xffff0000, v66
	v_lshlrev_b32_e32 v84, 16, v67
	v_and_b32_e32 v85, 0xffff0000, v67
	v_lshlrev_b32_e32 v86, 16, v68
	v_and_b32_e32 v87, 0xffff0000, v68
	v_lshlrev_b32_e32 v88, 16, v69
	v_and_b32_e32 v89, 0xffff0000, v69
	v_pk_add_f32 v[32:33], v[32:33], v[82:83] neg_lo:[0,1] neg_hi:[0,1]
	v_pk_add_f32 v[34:35], v[34:35], v[84:85] neg_lo:[0,1] neg_hi:[0,1]
	v_pk_add_f32 v[36:37], v[36:37], v[86:87] neg_lo:[0,1] neg_hi:[0,1]
	v_pk_add_f32 v[38:39], v[38:39], v[88:89] neg_lo:[0,1] neg_hi:[0,1]
.Lpl_sk_11:
	s_add_i32 s0, s99, 2
	s_min_i32 s0, s0, s41
	v_cvt_f32_u32_e32 v98, s0
	v_div_scale_f32 v99, s[100:101], v98, v98, 1.0
	v_rcp_f32_e32 v100, v99
	s_nop 0
	v_fma_f32 v101, -v99, v100, 1.0
	v_fmac_f32_e32 v100, v101, v100
	v_div_scale_f32 v101, vcc, 1.0, v98, 1.0
	v_mul_f32_e32 v102, v101, v100
	v_fma_f32 v103, -v99, v102, v101
	v_fmac_f32_e32 v102, v103, v100
	v_fma_f32 v99, -v99, v102, v101
	v_div_fmas_f32 v99, v99, v100, v102
	v_div_fixup_f32 v94, v99, v98, 1.0
	v_mov_b32_e32 v95, v94
	v_lshlrev_b32_e32 v40, 16, v54
	v_and_b32_e32 v41, 0xffff0000, v54
	v_lshlrev_b32_e32 v42, 16, v55
	v_and_b32_e32 v43, 0xffff0000, v55
	v_lshlrev_b32_e32 v44, 16, v56
	v_and_b32_e32 v45, 0xffff0000, v56
	v_lshlrev_b32_e32 v46, 16, v57
	v_and_b32_e32 v47, 0xffff0000, v57
	v_pk_add_f32 v[32:33], v[32:33], v[40:41]
	v_pk_add_f32 v[34:35], v[34:35], v[42:43]
	v_pk_add_f32 v[36:37], v[36:37], v[44:45]
	v_pk_add_f32 v[38:39], v[38:39], v[46:47]
	v_pk_fma_f32 v[82:83], v[32:33], v[94:95], v[40:41] neg_lo:[0,0,1] neg_hi:[0,0,1]
	v_pk_fma_f32 v[84:85], v[34:35], v[94:95], v[42:43] neg_lo:[0,0,1] neg_hi:[0,0,1]
	v_pk_fma_f32 v[86:87], v[36:37], v[94:95], v[44:45] neg_lo:[0,0,1] neg_hi:[0,0,1]
	v_pk_fma_f32 v[88:89], v[38:39], v[94:95], v[46:47] neg_lo:[0,0,1] neg_hi:[0,0,1]
	v_cvt_pk_bf16_f32 v90, v82, v83
	v_cvt_pk_bf16_f32 v91, v84, v85
	v_cvt_pk_bf16_f32 v92, v86, v87
	v_cvt_pk_bf16_f32 v93, v88, v89
	global_store_dwordx4 v48, v[90:93], s[22:23]
	s_add_u32 s22, s22, 0x1000
	s_addc_u32 s23, s23, 0
	s_add_i32 s0, s99, 1
	s_cmp_lt_i32 s0, s43
	s_cbranch_scc1 .Lpl_sk_12
	v_lshlrev_b32_e32 v82, 16, v70
	v_and_b32_e32 v83, 0xffff0000, v70
	v_lshlrev_b32_e32 v84, 16, v71
	v_and_b32_e32 v85, 0xffff0000, v71
	v_lshlrev_b32_e32 v86, 16, v72
	v_and_b32_e32 v87, 0xffff0000, v72
	v_lshlrev_b32_e32 v88, 16, v73
	v_and_b32_e32 v89, 0xffff0000, v73
	v_pk_add_f32 v[32:33], v[32:33], v[82:83] neg_lo:[0,1] neg_hi:[0,1]
	v_pk_add_f32 v[34:35], v[34:35], v[84:85] neg_lo:[0,1] neg_hi:[0,1]
	v_pk_add_f32 v[36:37], v[36:37], v[86:87] neg_lo:[0,1] neg_hi:[0,1]
	v_pk_add_f32 v[38:39], v[38:39], v[88:89] neg_lo:[0,1] neg_hi:[0,1]
.Lpl_sk_12:
	s_add_i32 s0, s99, 3
	s_min_i32 s0, s0, s41
	v_cvt_f32_u32_e32 v98, s0
	v_div_scale_f32 v99, s[100:101], v98, v98, 1.0
	v_rcp_f32_e32 v100, v99
	s_nop 0
	v_fma_f32 v101, -v99, v100, 1.0
	v_fmac_f32_e32 v100, v101, v100
	v_div_scale_f32 v101, vcc, 1.0, v98, 1.0
	v_mul_f32_e32 v102, v101, v100
	v_fma_f32 v103, -v99, v102, v101
	v_fmac_f32_e32 v102, v103, v100
	v_fma_f32 v99, -v99, v102, v101
	v_div_fmas_f32 v99, v99, v100, v102
	v_div_fixup_f32 v94, v99, v98, 1.0
	v_mov_b32_e32 v95, v94
	v_lshlrev_b32_e32 v40, 16, v58
	v_and_b32_e32 v41, 0xffff0000, v58
	v_lshlrev_b32_e32 v42, 16, v59
	v_and_b32_e32 v43, 0xffff0000, v59
	v_lshlrev_b32_e32 v44, 16, v60
	v_and_b32_e32 v45, 0xffff0000, v60
	v_lshlrev_b32_e32 v46, 16, v61
	v_and_b32_e32 v47, 0xffff0000, v61
	v_pk_add_f32 v[32:33], v[32:33], v[40:41]
	v_pk_add_f32 v[34:35], v[34:35], v[42:43]
	v_pk_add_f32 v[36:37], v[36:37], v[44:45]
	v_pk_add_f32 v[38:39], v[38:39], v[46:47]
	v_pk_fma_f32 v[82:83], v[32:33], v[94:95], v[40:41] neg_lo:[0,0,1] neg_hi:[0,0,1]
	v_pk_fma_f32 v[84:85], v[34:35], v[94:95], v[42:43] neg_lo:[0,0,1] neg_hi:[0,0,1]
	v_pk_fma_f32 v[86:87], v[36:37], v[94:95], v[44:45] neg_lo:[0,0,1] neg_hi:[0,0,1]
	v_pk_fma_f32 v[88:89], v[38:39], v[94:95], v[46:47] neg_lo:[0,0,1] neg_hi:[0,0,1]
	v_cvt_pk_bf16_f32 v90, v82, v83
	v_cvt_pk_bf16_f32 v91, v84, v85
	v_cvt_pk_bf16_f32 v92, v86, v87
	v_cvt_pk_bf16_f32 v93, v88, v89
	global_store_dwordx4 v48, v[90:93], s[22:23]
	s_add_u32 s22, s22, 0x1000
	s_addc_u32 s23, s23, 0
	s_add_i32 s0, s99, 2
	s_cmp_lt_i32 s0, s43
	s_cbranch_scc1 .Lpl_sk_13
	v_lshlrev_b32_e32 v82, 16, v74
	v_and_b32_e32 v83, 0xffff0000, v74
	v_lshlrev_b32_e32 v84, 16, v75
	v_and_b32_e32 v85, 0xffff0000, v75
	v_lshlrev_b32_e32 v86, 16, v76
	v_and_b32_e32 v87, 0xffff0000, v76
	v_lshlrev_b32_e32 v88, 16, v77
	v_and_b32_e32 v89, 0xffff0000, v77
	v_pk_add_f32 v[32:33], v[32:33], v[82:83] neg_lo:[0,1] neg_hi:[0,1]
	v_pk_add_f32 v[34:35], v[34:35], v[84:85] neg_lo:[0,1] neg_hi:[0,1]
	v_pk_add_f32 v[36:37], v[36:37], v[86:87] neg_lo:[0,1] neg_hi:[0,1]
	v_pk_add_f32 v[38:39], v[38:39], v[88:89] neg_lo:[0,1] neg_hi:[0,1]
.Lpl_sk_13:
	s_add_i32 s0, s99, 4
	s_min_i32 s0, s0, s41
	v_cvt_f32_u32_e32 v98, s0
	v_div_scale_f32 v99, s[100:101], v98, v98, 1.0
	v_rcp_f32_e32 v100, v99
	s_nop 0
	v_fma_f32 v101, -v99, v100, 1.0
	v_fmac_f32_e32 v100, v101, v100
	v_div_scale_f32 v101, vcc, 1.0, v98, 1.0
	v_mul_f32_e32 v102, v101, v100
	v_fma_f32 v103, -v99, v102, v101
	v_fmac_f32_e32 v102, v103, v100
	v_fma_f32 v99, -v99, v102, v101
	v_div_fmas_f32 v99, v99, v100, v102
	v_div_fixup_f32 v94, v99, v98, 1.0
	v_mov_b32_e32 v95, v94
	v_lshlrev_b32_e32 v40, 16, v62
	v_and_b32_e32 v41, 0xffff0000, v62
	v_lshlrev_b32_e32 v42, 16, v63
	v_and_b32_e32 v43, 0xffff0000, v63
	v_lshlrev_b32_e32 v44, 16, v64
	v_and_b32_e32 v45, 0xffff0000, v64
	v_lshlrev_b32_e32 v46, 16, v65
	v_and_b32_e32 v47, 0xffff0000, v65
	v_pk_add_f32 v[32:33], v[32:33], v[40:41]
	v_pk_add_f32 v[34:35], v[34:35], v[42:43]
	v_pk_add_f32 v[36:37], v[36:37], v[44:45]
	v_pk_add_f32 v[38:39], v[38:39], v[46:47]
	v_pk_fma_f32 v[82:83], v[32:33], v[94:95], v[40:41] neg_lo:[0,0,1] neg_hi:[0,0,1]
	v_pk_fma_f32 v[84:85], v[34:35], v[94:95], v[42:43] neg_lo:[0,0,1] neg_hi:[0,0,1]
	v_pk_fma_f32 v[86:87], v[36:37], v[94:95], v[44:45] neg_lo:[0,0,1] neg_hi:[0,0,1]
	v_pk_fma_f32 v[88:89], v[38:39], v[94:95], v[46:47] neg_lo:[0,0,1] neg_hi:[0,0,1]
	v_cvt_pk_bf16_f32 v90, v82, v83
	v_cvt_pk_bf16_f32 v91, v84, v85
	v_cvt_pk_bf16_f32 v92, v86, v87
	v_cvt_pk_bf16_f32 v93, v88, v89
	global_store_dwordx4 v48, v[90:93], s[22:23]
	s_add_u32 s22, s22, 0x1000
	s_addc_u32 s23, s23, 0
	s_add_i32 s0, s99, 3
	s_cmp_lt_i32 s0, s43
	s_cbranch_scc1 .Lpl_sk_14
	v_lshlrev_b32_e32 v82, 16, v78
	v_and_b32_e32 v83, 0xffff0000, v78
	v_lshlrev_b32_e32 v84, 16, v79
	v_and_b32_e32 v85, 0xffff0000, v79
	v_lshlrev_b32_e32 v86, 16, v80
	v_and_b32_e32 v87, 0xffff0000, v80
	v_lshlrev_b32_e32 v88, 16, v81
	v_and_b32_e32 v89, 0xffff0000, v81
	v_pk_add_f32 v[32:33], v[32:33], v[82:83] neg_lo:[0,1] neg_hi:[0,1]
	v_pk_add_f32 v[34:35], v[34:35], v[84:85] neg_lo:[0,1] neg_hi:[0,1]
	v_pk_add_f32 v[36:37], v[36:37], v[86:87] neg_lo:[0,1] neg_hi:[0,1]
	v_pk_add_f32 v[38:39], v[38:39], v[88:89] neg_lo:[0,1] neg_hi:[0,1]
.Lpl_sk_14:
	s_add_i32 s46, s40, 12
	s_add_i32 s0, s48, -4
	s_min_i32 s46, s46, s0
	s_add_i32 s0, s42, s46
	s_lshl_b32 s0, s0, 13
	s_add_u32 s8, s4, s0
	s_addc_u32 s9, s5, 0
	global_load_dwordx4 v[50:53], v48, s[8:9]
	s_add_u32 s8, s8, 0x2000
	s_addc_u32 s9, s9, 0
	global_load_dwordx4 v[54:57], v48, s[8:9]
	s_add_u32 s8, s8, 0x2000
	s_addc_u32 s9, s9, 0
	global_load_dwordx4 v[58:61], v48, s[8:9]
	s_add_u32 s8, s8, 0x2000
	s_addc_u32 s9, s9, 0
	global_load_dwordx4 v[62:65], v48, s[8:9]
	s_sub_i32 s1, s46, s43
	s_add_i32 s0, s1, 0
	s_max_i32 s0, s0, 0
	s_add_i32 s0, s0, s42
	s_lshl_b32 s0, s0, 13
	s_add_u32 s10, s4, s0
	s_addc_u32 s11, s5, 0
	global_load_dwordx4 v[66:69], v48, s[10:11]
	s_add_i32 s0, s1, 1
	s_max_i32 s0, s0, 0
	s_add_i32 s0, s0, s42
	s_lshl_b32 s0, s0, 13
	s_add_u32 s10, s4, s0
	s_addc_u32 s11, s5, 0
	global_load_dwordx4 v[70:73], v48, s[10:11]
	s_add_i32 s0, s1, 2
	s_max_i32 s0, s0, 0
	s_add_i32 s0, s0, s42
	s_lshl_b32 s0, s0, 13
	s_add_u32 s10, s4, s0
	s_addc_u32 s11, s5, 0
	global_load_dwordx4 v[74:77], v48, s[10:11]
	s_add_i32 s0, s1, 3
	s_max_i32 s0, s0, 0
	s_add_i32 s0, s0, s42
	s_lshl_b32 s0, s0, 13
	s_add_u32 s10, s4, s0
	s_addc_u32 s11, s5, 0
	global_load_dwordx4 v[78:81], v48, s[10:11]
	s_waitcnt vmcnt(12)
	s_add_i32 s40, s40, 8
	s_cmp_lt_i32 s40, s48
	s_cbranch_scc1 .Lpl_loop_6
	s_cmp_lt_u32 s49, 0x8000
	s_cbranch_scc0 .Lpl_done_15
	s_waitcnt vmcnt(0)
	s_lshr_b32 s1, s49, 8
	s_lshl_b32 s0, s1, 3
	s_add_i32 s42, s0, 0x4000
	s_add_i32 s0, s21, s1
	s_mul_i32 s99, s0, 15
	s_lshl_b32 s0, s42, 12
	s_add_u32 s22, s70, s0
	s_addc_u32 s23, s71, 0
	s_lshl_b32 s0, s42, 13
	s_add_u32 s8, s4, s0
	s_addc_u32 s9, s5, 0
	global_load_dwordx4 v[0:3], v48, s[8:9]
	s_add_u32 s8, s8, 0x2000
	s_addc_u32 s9, s9, 0
	global_load_dwordx4 v[4:7], v48, s[8:9]
	s_add_u32 s8, s8, 0x2000
	s_addc_u32 s9, s9, 0
	global_load_dwordx4 v[8:11], v48, s[8:9]
	s_add_u32 s8, s8, 0x2000
	s_addc_u32 s9, s9, 0
	global_load_dwordx4 v[12:15], v48, s[8:9]
	s_add_u32 s8, s8, 0x2000
	s_addc_u32 s9, s9, 0
	global_load_dwordx4 v[16:19], v48, s[8:9]
	s_add_u32 s8, s8, 0x2000
	s_addc_u32 s9, s9, 0
	global_load_dwordx4 v[20:23], v48, s[8:9]
	s_add_u32 s8, s8, 0x2000
	s_addc_u32 s9, s9, 0
	global_load_dwordx4 v[24:27], v48, s[8:9]
	s_add_u32 s8, s8, 0x2000
	s_addc_u32 s9, s9, 0
	global_load_dwordx4 v[28:31], v48, s[8:9]
	v_mov_b32_e32 v32, 0
	v_mov_b32_e32 v33, 0
	v_mov_b32_e32 v34, 0
	v_mov_b32_e32 v35, 0
	v_mov_b32_e32 v36, 0
	v_mov_b32_e32 v37, 0
	v_mov_b32_e32 v38, 0
	v_mov_b32_e32 v39, 0
	s_mov_b32 s40, 1
.Lpl_sw_16:
	s_add_i32 s1, s40, 0
	s_cmp_gt_i32 s1, s43
	s_cbranch_scc1 .Lpl_swl_17
	s_sub_i32 s1, 15, s1
	s_add_i32 s0, s99, s1
	s_lshl_b32 s0, s0, 13
	s_add_u32 s10, s36, s0
	s_addc_u32 s11, s37, 0
	global_load_dwordx4 v[50:53], v114, s[10:11]
	global_load_dwordx4 v[54:57], v114, s[10:11] offset:16
.Lpl_swl_17:
	s_add_i32 s1, s40, 1
	s_cmp_gt_i32 s1, s43
	s_cbranch_scc1 .Lpl_swl_18
	s_sub_i32 s1, 15, s1
	s_add_i32 s0, s99, s1
	s_lshl_b32 s0, s0, 13
	s_add_u32 s10, s36, s0
	s_addc_u32 s11, s37, 0
	global_load_dwordx4 v[58:61], v114, s[10:11]
	global_load_dwordx4 v[62:65], v114, s[10:11] offset:16
.Lpl_swl_18:
	s_add_i32 s1, s40, 2
	s_cmp_gt_i32 s1, s43
	s_cbranch_scc1 .Lpl_swl_19
	s_sub_i32 s1, 15, s1
	s_add_i32 s0, s99, s1
	s_lshl_b32 s0, s0, 13
	s_add_u32 s10, s36, s0
	s_addc_u32 s11, s37, 0
	global_load_dwordx4 v[66:69], v114, s[10:11]
	global_load_dwordx4 v[70:73], v114, s[10:11] offset:16
.Lpl_swl_19:
	s_add_i32 s1, s40, 3
	s_cmp_gt_i32 s1, s43
	s_cbranch_scc1 .Lpl_swl_20
	s_sub_i32 s1, 15, s1
	s_add_i32 s0, s99, s1
	s_lshl_b32 s0, s0, 13
	s_add_u32 s10, s36, s0
	s_addc_u32 s11, s37, 0
	global_load_dwordx4 v[74:77], v114, s[10:11]
	global_load_dwordx4 v[78:81], v114, s[10:11] offset:16
.Lpl_swl_20:
	s_waitcnt vmcnt(0)
	s_add_i32 s1, s40, 0
	s_cmp_gt_i32 s1, s43
	s_cbranch_scc1 .Lpl_swa_21
	v_pk_add_f32 v[32:33], v[32:33], v[50:51]
	v_pk_add_f32 v[34:35], v[34:35], v[52:53]
	v_pk_add_f32 v[36:37], v[36:37], v[54:55]
	v_pk_add_f32 v[38:39], v[38:39], v[56:57]
.Lpl_swa_21:
	s_add_i32 s1, s40, 1
	s_cmp_gt_i32 s1, s43
	s_cbranch_scc1 .Lpl_swa_22
	v_pk_add_f32 v[32:33], v[32:33], v[58:59]
	v_pk_add_f32 v[34:35], v[34:35], v[60:61]
	v_pk_add_f32 v[36:37], v[36:37], v[62:63]
	v_pk_add_f32 v[38:39], v[38:39], v[64:65]
.Lpl_swa_22:
	s_add_i32 s1, s40, 2
	s_cmp_gt_i32 s1, s43
	s_cbranch_scc1 .Lpl_swa_23
	v_pk_add_f32 v[32:33], v[32:33], v[66:67]
	v_pk_add_f32 v[34:35], v[34:35], v[68:69]
	v_pk_add_f32 v[36:37], v[36:37], v[70:71]
	v_pk_add_f32 v[38:39], v[38:39], v[72:73]
.Lpl_swa_23:
	s_add_i32 s1, s40, 3
	s_cmp_gt_i32 s1, s43
	s_cbranch_scc1 .Lpl_swa_24
	v_pk_add_f32 v[32:33], v[32:33], v[74:75]
	v_pk_add_f32 v[34:35], v[34:35], v[76:77]
	v_pk_add_f32 v[36:37], v[36:37], v[78:79]
	v_pk_add_f32 v[38:39], v[38:39], v[80:81]
.Lpl_swa_24:
	s_add_i32 s40, s40, 4
	s_cmp_le_i32 s40, s43
	s_cbranch_scc1 .Lpl_sw_16
	v_cvt_f32_u32_e32 v98, s41
	v_div_scale_f32 v99, s[100:101], v98, v98, 1.0
	v_rcp_f32_e32 v100, v99
	s_nop 0
	v_fma_f32 v101, -v99, v100, 1.0
	v_fmac_f32_e32 v100, v101, v100
	v_div_scale_f32 v101, vcc, 1.0, v98, 1.0
	v_mul_f32_e32 v102, v101, v100
	v_fma_f32 v103, -v99, v102, v101
	v_fmac_f32_e32 v102, v103, v100
	v_fma_f32 v99, -v99, v102, v101
	v_div_fmas_f32 v99, v99, v100, v102
	v_div_fixup_f32 v94, v99, v98, 1.0
	v_mov_b32_e32 v95, v94
	s_cmp_lt_i32 s43, 1
	s_cbranch_scc1 .Lpl_of_25
	s_sub_i32 s1, 15, s43
	s_add_i32 s0, s99, s1
	s_lshl_b32 s0, s0, 13
	s_add_u32 s10, s36, s0
	s_addc_u32 s11, s37, 0
	global_load_dwordx4 v[50:53], v114, s[10:11]
	global_load_dwordx4 v[54:57], v114, s[10:11] offset:16
	s_branch .Lpl_oe_26
.Lpl_of_25:
	s_sub_i32 s0, 0, s43
	s_add_i32 s0, s0, s42
	s_lshl_b32 s0, s0, 13
	s_add_u32 s10, s4, s0
	s_addc_u32 s11, s5, 0
	global_load_dwordx4 v[50:53], v48, s[10:11]
.Lpl_oe_26:
	s_cmp_lt_i32 s43, 2
	s_cbranch_scc1 .Lpl_of_27
	s_sub_i32 s1, 16, s43
	s_add_i32 s0, s99, s1
	s_lshl_b32 s0, s0, 13
	s_add_u32 s10, s36, s0
	s_addc_u32 s11, s37, 0
	global_load_dwordx4 v[58:61], v114, s[10:11]
	global_load_dwordx4 v[62:65], v114, s[10:11] offset:16
	s_branch .Lpl_oe_28
.Lpl_of_27:
	s_sub_i32 s0, 1, s43
	s_add_i32 s0, s0, s42
	s_lshl_b32 s0, s0, 13
	s_add_u32 s10, s4, s0
	s_addc_u32 s11, s5, 0
	global_load_dwordx4 v[58:61], v48, s[10:11]
.Lpl_oe_28:
	s_cmp_lt_i32 s43, 3
	s_cbranch_scc1 .Lpl_of_29
	s_sub_i32 s1, 17, s43
	s_add_i32 s0, s99, s1
	s_lshl_b32 s0, s0, 13
	s_add_u32 s10, s36, s0
	s_addc_u32 s11, s37, 0
	global_load_dwordx4 v[66:69], v114, s[10:11]
	global_load_dwordx4 v[70:73], v114, s[10:11] offset:16
	s_branch .Lpl_oe_30
.Lpl_of_29:
	s_sub_i32 s0, 2, s43
	s_add_i32 s0, s0, s42
	s_lshl_b32 s0, s0, 13
	s_add_u32 s10, s4, s0
	s_addc_u32 s11, s5, 0
	global_load_dwordx4 v[66:69], v48, s[10:11]
.Lpl_oe_30:
	s_cmp_lt_i32 s43, 4
	s_cbranch_scc1 .Lpl_of_31
	s_sub_i32 s1, 18, s43
	s_add_i32 s0, s99, s1
	s_lshl_b32 s0, s0, 13
	s_add_u32 s10, s36, s0
	s_addc_u32 s11, s37, 0
	global_load_dwordx4 v[74:77], v114, s[10:11]
	global_load_dwordx4 v[78:81], v114, s[10:11] offset:16
	s_branch .Lpl_oe_32
.Lpl_of_31:
	s_sub_i32 s0, 3, s43
	s_add_i32 s0, s0, s42
	s_lshl_b32 s0, s0, 13
	s_add_u32 s10, s4, s0
	s_addc_u32 s11, s5, 0
	global_load_dwordx4 v[74:77], v48, s[10:11]
.Lpl_oe_32:
	s_waitcnt vmcnt(0)
	v_lshlrev_b32_e32 v40, 16, v0
	v_and_b32_e32 v41, 0xffff0000, v0
	v_lshlrev_b32_e32 v42, 16, v1
	v_and_b32_e32 v43, 0xffff0000, v1
	v_lshlrev_b32_e32 v44, 16, v2
	v_and_b32_e32 v45, 0xffff0000, v2
	v_lshlrev_b32_e32 v46, 16, v3
	v_and_b32_e32 v47, 0xffff0000, v3
	v_pk_add_f32 v[32:33], v[32:33], v[40:41]
	v_pk_add_f32 v[34:35], v[34:35], v[42:43]
	v_pk_add_f32 v[36:37], v[36:37], v[44:45]
	v_pk_add_f32 v[38:39], v[38:39], v[46:47]
	v_pk_fma_f32 v[82:83], v[32:33], v[94:95], v[40:41] neg_lo:[0,0,1] neg_hi:[0,0,1]
	v_pk_fma_f32 v[84:85], v[34:35], v[94:95], v[42:43] neg_lo:[0,0,1] neg_hi:[0,0,1]
	v_pk_fma_f32 v[86:87], v[36:37], v[94:95], v[44:45] neg_lo:[0,0,1] neg_hi:[0,0,1]
	v_pk_fma_f32 v[88:89], v[38:39], v[94:95], v[46:47] neg_lo:[0,0,1] neg_hi:[0,0,1]
	v_cvt_pk_bf16_f32 v90, v82, v83
	v_cvt_pk_bf16_f32 v91, v84, v85
	v_cvt_pk_bf16_f32 v92, v86, v87
	v_cvt_pk_bf16_f32 v93, v88, v89
	global_store_dwordx4 v48, v[90:93], s[22:23]
	s_add_u32 s22, s22, 0x1000
	s_addc_u32 s23, s23, 0
	s_cmp_lt_i32 s43, 1
	s_cbranch_scc1 .Lpl_sf_33
	v_pk_add_f32 v[32:33], v[32:33], v[50:51] neg_lo:[0,1] neg_hi:[0,1]
	v_pk_add_f32 v[34:35], v[34:35], v[52:53] neg_lo:[0,1] neg_hi:[0,1]
	v_pk_add_f32 v[36:37], v[36:37], v[54:55] neg_lo:[0,1] neg_hi:[0,1]
	v_pk_add_f32 v[38:39], v[38:39], v[56:57] neg_lo:[0,1] neg_hi:[0,1]
	s_branch .Lpl_se_34
.Lpl_sf_33:
	v_lshlrev_b32_e32 v82, 16, v50
	v_and_b32_e32 v83, 0xffff0000, v50
	v_lshlrev_b32_e32 v84, 16, v51
	v_and_b32_e32 v85, 0xffff0000, v51
	v_lshlrev_b32_e32 v86, 16, v52
	v_and_b32_e32 v87, 0xffff0000, v52
	v_lshlrev_b32_e32 v88, 16, v53
	v_and_b32_e32 v89, 0xffff0000, v53
	v_pk_add_f32 v[32:33], v[32:33], v[82:83] neg_lo:[0,1] neg_hi:[0,1]
	v_pk_add_f32 v[34:35], v[34:35], v[84:85] neg_lo:[0,1] neg_hi:[0,1]
	v_pk_add_f32 v[36:37], v[36:37], v[86:87] neg_lo:[0,1] neg_hi:[0,1]
	v_pk_add_f32 v[38:39], v[38:39], v[88:89] neg_lo:[0,1] neg_hi:[0,1]
.Lpl_se_34:
	v_lshlrev_b32_e32 v40, 16, v4
	v_and_b32_e32 v41, 0xffff0000, v4
	v_lshlrev_b32_e32 v42, 16, v5
	v_and_b32_e32 v43, 0xffff0000, v5
	v_lshlrev_b32_e32 v44, 16, v6
	v_and_b32_e32 v45, 0xffff0000, v6
	v_lshlrev_b32_e32 v46, 16, v7
	v_and_b32_e32 v47, 0xffff0000, v7
	v_pk_add_f32 v[32:33], v[32:33], v[40:41]
	v_pk_add_f32 v[34:35], v[34:35], v[42:43]
	v_pk_add_f32 v[36:37], v[36:37], v[44:45]
	v_pk_add_f32 v[38:39], v[38:39], v[46:47]
	v_pk_fma_f32 v[82:83], v[32:33], v[94:95], v[40:41] neg_lo:[0,0,1] neg_hi:[0,0,1]
	v_pk_fma_f32 v[84:85], v[34:35], v[94:95], v[42:43] neg_lo:[0,0,1] neg_hi:[0,0,1]
	v_pk_fma_f32 v[86:87], v[36:37], v[94:95], v[44:45] neg_lo:[0,0,1] neg_hi:[0,0,1]
	v_pk_fma_f32 v[88:89], v[38:39], v[94:95], v[46:47] neg_lo:[0,0,1] neg_hi:[0,0,1]
	v_cvt_pk_bf16_f32 v90, v82, v83
	v_cvt_pk_bf16_f32 v91, v84, v85
	v_cvt_pk_bf16_f32 v92, v86, v87
	v_cvt_pk_bf16_f32 v93, v88, v89
	global_store_dwordx4 v48, v[90:93], s[22:23]
	s_add_u32 s22, s22, 0x1000
	s_addc_u32 s23, s23, 0
	s_cmp_lt_i32 s43, 2
	s_cbranch_scc1 .Lpl_sf_35
	v_pk_add_f32 v[32:33], v[32:33], v[58:59] neg_lo:[0,1] neg_hi:[0,1]
	v_pk_add_f32 v[34:35], v[34:35], v[60:61] neg_lo:[0,1] neg_hi:[0,1]
	v_pk_add_f32 v[36:37], v[36:37], v[62:63] neg_lo:[0,1] neg_hi:[0,1]
	v_pk_add_f32 v[38:39], v[38:39], v[64:65] neg_lo:[0,1] neg_hi:[0,1]
	s_branch .Lpl_se_36
.Lpl_sf_35:
	v_lshlrev_b32_e32 v82, 16, v58
	v_and_b32_e32 v83, 0xffff0000, v58
	v_lshlrev_b32_e32 v84, 16, v59
	v_and_b32_e32 v85, 0xffff0000, v59
	v_lshlrev_b32_e32 v86, 16, v60
	v_and_b32_e32 v87, 0xffff0000, v60
	v_lshlrev_b32_e32 v88, 16, v61
	v_and_b32_e32 v89, 0xffff0000, v61
	v_pk_add_f32 v[32:33], v[32:33], v[82:83] neg_lo:[0,1] neg_hi:[0,1]
	v_pk_add_f32 v[34:35], v[34:35], v[84:85] neg_lo:[0,1] neg_hi:[0,1]
	v_pk_add_f32 v[36:37], v[36:37], v[86:87] neg_lo:[0,1] neg_hi:[0,1]
	v_pk_add_f32 v[38:39], v[38:39], v[88:89] neg_lo:[0,1] neg_hi:[0,1]
.Lpl_se_36:
	v_lshlrev_b32_e32 v40, 16, v8
	v_and_b32_e32 v41, 0xffff0000, v8
	v_lshlrev_b32_e32 v42, 16, v9
	v_and_b32_e32 v43, 0xffff0000, v9
	v_lshlrev_b32_e32 v44, 16, v10
	v_and_b32_e32 v45, 0xffff0000, v10
	v_lshlrev_b32_e32 v46, 16, v11
	v_and_b32_e32 v47, 0xffff0000, v11
	v_pk_add_f32 v[32:33], v[32:33], v[40:41]
	v_pk_add_f32 v[34:35], v[34:35], v[42:43]
	v_pk_add_f32 v[36:37], v[36:37], v[44:45]
	v_pk_add_f32 v[38:39], v[38:39], v[46:47]
	v_pk_fma_f32 v[82:83], v[32:33], v[94:95], v[40:41] neg_lo:[0,0,1] neg_hi:[0,0,1]
	v_pk_fma_f32 v[84:85], v[34:35], v[94:95], v[42:43] neg_lo:[0,0,1] neg_hi:[0,0,1]
	v_pk_fma_f32 v[86:87], v[36:37], v[94:95], v[44:45] neg_lo:[0,0,1] neg_hi:[0,0,1]
	v_pk_fma_f32 v[88:89], v[38:39], v[94:95], v[46:47] neg_lo:[0,0,1] neg_hi:[0,0,1]
	v_cvt_pk_bf16_f32 v90, v82, v83
	v_cvt_pk_bf16_f32 v91, v84, v85
	v_cvt_pk_bf16_f32 v92, v86, v87
	v_cvt_pk_bf16_f32 v93, v88, v89
	global_store_dwordx4 v48, v[90:93], s[22:23]
	s_add_u32 s22, s22, 0x1000
	s_addc_u32 s23, s23, 0
	s_cmp_lt_i32 s43, 3
	s_cbranch_scc1 .Lpl_sf_37
	v_pk_add_f32 v[32:33], v[32:33], v[66:67] neg_lo:[0,1] neg_hi:[0,1]
	v_pk_add_f32 v[34:35], v[34:35], v[68:69] neg_lo:[0,1] neg_hi:[0,1]
	v_pk_add_f32 v[36:37], v[36:37], v[70:71] neg_lo:[0,1] neg_hi:[0,1]
	v_pk_add_f32 v[38:39], v[38:39], v[72:73] neg_lo:[0,1] neg_hi:[0,1]
	s_branch .Lpl_se_38
.Lpl_sf_37:
	v_lshlrev_b32_e32 v82, 16, v66
	v_and_b32_e32 v83, 0xffff0000, v66
	v_lshlrev_b32_e32 v84, 16, v67
	v_and_b32_e32 v85, 0xffff0000, v67
	v_lshlrev_b32_e32 v86, 16, v68
	v_and_b32_e32 v87, 0xffff0000, v68
	v_lshlrev_b32_e32 v88, 16, v69
	v_and_b32_e32 v89, 0xffff0000, v69
	v_pk_add_f32 v[32:33], v[32:33], v[82:83] neg_lo:[0,1] neg_hi:[0,1]
	v_pk_add_f32 v[34:35], v[34:35], v[84:85] neg_lo:[0,1] neg_hi:[0,1]
	v_pk_add_f32 v[36:37], v[36:37], v[86:87] neg_lo:[0,1] neg_hi:[0,1]
	v_pk_add_f32 v[38:39], v[38:39], v[88:89] neg_lo:[0,1] neg_hi:[0,1]
.Lpl_se_38:
	v_lshlrev_b32_e32 v40, 16, v12
	v_and_b32_e32 v41, 0xffff0000, v12
	v_lshlrev_b32_e32 v42, 16, v13
	v_and_b32_e32 v43, 0xffff0000, v13
	v_lshlrev_b32_e32 v44, 16, v14
	v_and_b32_e32 v45, 0xffff0000, v14
	v_lshlrev_b32_e32 v46, 16, v15
	v_and_b32_e32 v47, 0xffff0000, v15
	v_pk_add_f32 v[32:33], v[32:33], v[40:41]
	v_pk_add_f32 v[34:35], v[34:35], v[42:43]
	v_pk_add_f32 v[36:37], v[36:37], v[44:45]
	v_pk_add_f32 v[38:39], v[38:39], v[46:47]
	v_pk_fma_f32 v[82:83], v[32:33], v[94:95], v[40:41] neg_lo:[0,0,1] neg_hi:[0,0,1]
	v_pk_fma_f32 v[84:85], v[34:35], v[94:95], v[42:43] neg_lo:[0,0,1] neg_hi:[0,0,1]
	v_pk_fma_f32 v[86:87], v[36:37], v[94:95], v[44:45] neg_lo:[0,0,1] neg_hi:[0,0,1]
	v_pk_fma_f32 v[88:89], v[38:39], v[94:95], v[46:47] neg_lo:[0,0,1] neg_hi:[0,0,1]
	v_cvt_pk_bf16_f32 v90, v82, v83
	v_cvt_pk_bf16_f32 v91, v84, v85
	v_cvt_pk_bf16_f32 v92, v86, v87
	v_cvt_pk_bf16_f32 v93, v88, v89
	global_store_dwordx4 v48, v[90:93], s[22:23]
	s_add_u32 s22, s22, 0x1000
	s_addc_u32 s23, s23, 0
	s_cmp_lt_i32 s43, 4
	s_cbranch_scc1 .Lpl_sf_39
	v_pk_add_f32 v[32:33], v[32:33], v[74:75] neg_lo:[0,1] neg_hi:[0,1]
	v_pk_add_f32 v[34:35], v[34:35], v[76:77] neg_lo:[0,1] neg_hi:[0,1]
	v_pk_add_f32 v[36:37], v[36:37], v[78:79] neg_lo:[0,1] neg_hi:[0,1]
	v_pk_add_f32 v[38:39], v[38:39], v[80:81] neg_lo:[0,1] neg_hi:[0,1]
	s_branch .Lpl_se_40
.Lpl_sf_39:
	v_lshlrev_b32_e32 v82, 16, v74
	v_and_b32_e32 v83, 0xffff0000, v74
	v_lshlrev_b32_e32 v84, 16, v75
	v_and_b32_e32 v85, 0xffff0000, v75
	v_lshlrev_b32_e32 v86, 16, v76
	v_and_b32_e32 v87, 0xffff0000, v76
	v_lshlrev_b32_e32 v88, 16, v77
	v_and_b32_e32 v89, 0xffff0000, v77
	v_pk_add_f32 v[32:33], v[32:33], v[82:83] neg_lo:[0,1] neg_hi:[0,1]
	v_pk_add_f32 v[34:35], v[34:35], v[84:85] neg_lo:[0,1] neg_hi:[0,1]
	v_pk_add_f32 v[36:37], v[36:37], v[86:87] neg_lo:[0,1] neg_hi:[0,1]
	v_pk_add_f32 v[38:39], v[38:39], v[88:89] neg_lo:[0,1] neg_hi:[0,1]
.Lpl_se_40:
	s_cmp_lt_i32 s43, 5
	s_cbranch_scc1 .Lpl_of_41
	s_sub_i32 s1, 19, s43
	s_add_i32 s0, s99, s1
	s_lshl_b32 s0, s0, 13
	s_add_u32 s10, s36, s0
	s_addc_u32 s11, s37, 0
	global_load_dwordx4 v[50:53], v114, s[10:11]
	global_load_dwordx4 v[54:57], v114, s[10:11] offset:16
	s_branch .Lpl_oe_42
.Lpl_of_41:
	s_sub_i32 s0, 4, s43
	s_add_i32 s0, s0, s42
	s_lshl_b32 s0, s0, 13
	s_add_u32 s10, s4, s0
	s_addc_u32 s11, s5, 0
	global_load_dwordx4 v[50:53], v48, s[10:11]
.Lpl_oe_42:
	s_cmp_lt_i32 s43, 6
	s_cbranch_scc1 .Lpl_of_43
	s_sub_i32 s1, 20, s43
	s_add_i32 s0, s99, s1
	s_lshl_b32 s0, s0, 13
	s_add_u32 s10, s36, s0
	s_addc_u32 s11, s37, 0
	global_load_dwordx4 v[58:61], v114, s[10:11]
	global_load_dwordx4 v[62:65], v114, s[10:11] offset:16
	s_branch .Lpl_oe_44
.Lpl_of_43:
	s_sub_i32 s0, 5, s43
	s_add_i32 s0, s0, s42
	s_lshl_b32 s0, s0, 13
	s_add_u32 s10, s4, s0
	s_addc_u32 s11, s5, 0
	global_load_dwordx4 v[58:61], v48, s[10:11]
.Lpl_oe_44:
	s_cmp_lt_i32 s43, 7
	s_cbranch_scc1 .Lpl_of_45
	s_sub_i32 s1, 21, s43
	s_add_i32 s0, s99, s1
	s_lshl_b32 s0, s0, 13
	s_add_u32 s10, s36, s0
	s_addc_u32 s11, s37, 0
	global_load_dwordx4 v[66:69], v114, s[10:11]
	global_load_dwordx4 v[70:73], v114, s[10:11] offset:16
	s_branch .Lpl_oe_46
.Lpl_of_45:
	s_sub_i32 s0, 6, s43
	s_add_i32 s0, s0, s42
	s_lshl_b32 s0, s0, 13
	s_add_u32 s10, s4, s0
	s_addc_u32 s11, s5, 0
	global_load_dwordx4 v[66:69], v48, s[10:11]
.Lpl_oe_46:
	s_cmp_lt_i32 s43, 8
	s_cbranch_scc1 .Lpl_of_47
	s_sub_i32 s1, 22, s43
	s_add_i32 s0, s99, s1
	s_lshl_b32 s0, s0, 13
	s_add_u32 s10, s36, s0
	s_addc_u32 s11, s37, 0
	global_load_dwordx4 v[74:77], v114, s[10:11]
	global_load_dwordx4 v[78:81], v114, s[10:11] offset:16
	s_branch .Lpl_oe_48
.Lpl_of_47:
	s_sub_i32 s0, 7, s43
	s_add_i32 s0, s0, s42
	s_lshl_b32 s0, s0, 13
	s_add_u32 s10, s4, s0
	s_addc_u32 s11, s5, 0
	global_load_dwordx4 v[74:77], v48, s[10:11]
.Lpl_oe_48:
	s_waitcnt vmcnt(0)
	v_lshlrev_b32_e32 v40, 16, v16
	v_and_b32_e32 v41, 0xffff0000, v16
	v_lshlrev_b32_e32 v42, 16, v17
	v_and_b32_e32 v43, 0xffff0000, v17
	v_lshlrev_b32_e32 v44, 16, v18
	v_and_b32_e32 v45, 0xffff0000, v18
	v_lshlrev_b32_e32 v46, 16, v19
	v_and_b32_e32 v47, 0xffff0000, v19
	v_pk_add_f32 v[32:33], v[32:33], v[40:41]
	v_pk_add_f32 v[34:35], v[34:35], v[42:43]
	v_pk_add_f32 v[36:37], v[36:37], v[44:45]
	v_pk_add_f32 v[38:39], v[38:39], v[46:47]
	v_pk_fma_f32 v[82:83], v[32:33], v[94:95], v[40:41] neg_lo:[0,0,1] neg_hi:[0,0,1]
	v_pk_fma_f32 v[84:85], v[34:35], v[94:95], v[42:43] neg_lo:[0,0,1] neg_hi:[0,0,1]
	v_pk_fma_f32 v[86:87], v[36:37], v[94:95], v[44:45] neg_lo:[0,0,1] neg_hi:[0,0,1]
	v_pk_fma_f32 v[88:89], v[38:39], v[94:95], v[46:47] neg_lo:[0,0,1] neg_hi:[0,0,1]
	v_cvt_pk_bf16_f32 v90, v82, v83
	v_cvt_pk_bf16_f32 v91, v84, v85
	v_cvt_pk_bf16_f32 v92, v86, v87
	v_cvt_pk_bf16_f32 v93, v88, v89
	global_store_dwordx4 v48, v[90:93], s[22:23]
	s_add_u32 s22, s22, 0x1000
	s_addc_u32 s23, s23, 0
	s_cmp_lt_i32 s43, 5
	s_cbranch_scc1 .Lpl_sf_49
	v_pk_add_f32 v[32:33], v[32:33], v[50:51] neg_lo:[0,1] neg_hi:[0,1]
	v_pk_add_f32 v[34:35], v[34:35], v[52:53] neg_lo:[0,1] neg_hi:[0,1]
	v_pk_add_f32 v[36:37], v[36:37], v[54:55] neg_lo:[0,1] neg_hi:[0,1]
	v_pk_add_f32 v[38:39], v[38:39], v[56:57] neg_lo:[0,1] neg_hi:[0,1]
	s_branch .Lpl_se_50

.Lpl_se_50:
	v_lshlrev_b32_e32 v40, 16, v20
	v_and_b32_e32 v41, 0xffff0000, v20
	v_lshlrev_b32_e32 v42, 16, v21
	v_and_b32_e32 v43, 0xffff0000, v21
	v_lshlrev_b32_e32 v44, 16, v22
	v_and_b32_e32 v45, 0xffff0000, v22
	v_lshlrev_b32_e32 v46, 16, v23
	v_and_b32_e32 v47, 0xffff0000, v23
	v_pk_add_f32 v[32:33], v[32:33], v[40:41]
	v_pk_add_f32 v[34:35], v[34:35], v[42:43]
	v_pk_add_f32 v[36:37], v[36:37], v[44:45]
	v_pk_add_f32 v[38:39], v[38:39], v[46:47]
	v_pk_fma_f32 v[82:83], v[32:33], v[94:95], v[40:41] neg_lo:[0,0,1] neg_hi:[0,0,1]
	v_pk_fma_f32 v[84:85], v[34:35], v[94:95], v[42:43] neg_lo:[0,0,1] neg_hi:[0,0,1]
	v_pk_fma_f32 v[86:87], v[36:37], v[94:95], v[44:45] neg_lo:[0,0,1] neg_hi:[0,0,1]
	v_pk_fma_f32 v[88:89], v[38:39], v[94:95], v[46:47] neg_lo:[0,0,1] neg_hi:[0,0,1]
	v_cvt_pk_bf16_f32 v90, v82, v83
	v_cvt_pk_bf16_f32 v91, v84, v85
	v_cvt_pk_bf16_f32 v92, v86, v87
	v_cvt_pk_bf16_f32 v93, v88, v89
	global_store_dwordx4 v48, v[90:93], s[22:23]
	s_add_u32 s22, s22, 0x1000
	s_addc_u32 s23, s23, 0
	s_cmp_lt_i32 s43, 6
	s_cbranch_scc1 .Lpl_sf_51
	v_pk_add_f32 v[32:33], v[32:33], v[58:59] neg_lo:[0,1] neg_hi:[0,1]
	v_pk_add_f32 v[34:35], v[34:35], v[60:61] neg_lo:[0,1] neg_hi:[0,1]
	v_pk_add_f32 v[36:37], v[36:37], v[62:63] neg_lo:[0,1] neg_hi:[0,1]
	v_pk_add_f32 v[38:39], v[38:39], v[64:65] neg_lo:[0,1] neg_hi:[0,1]
	s_branch .Lpl_se_52

.Lpl_se_52:
	v_lshlrev_b32_e32 v40, 16, v24
	v_and_b32_e32 v41, 0xffff0000, v24
	v_lshlrev_b32_e32 v42, 16, v25
	v_and_b32_e32 v43, 0xffff0000, v25
	v_lshlrev_b32_e32 v44, 16, v26
	v_and_b32_e32 v45, 0xffff0000, v26
	v_lshlrev_b32_e32 v46, 16, v27
	v_and_b32_e32 v47, 0xffff0000, v27
	v_pk_add_f32 v[32:33], v[32:33], v[40:41]
	v_pk_add_f32 v[34:35], v[34:35], v[42:43]
	v_pk_add_f32 v[36:37], v[36:37], v[44:45]
	v_pk_add_f32 v[38:39], v[38:39], v[46:47]
	v_pk_fma_f32 v[82:83], v[32:33], v[94:95], v[40:41] neg_lo:[0,0,1] neg_hi:[0,0,1]
	v_pk_fma_f32 v[84:85], v[34:35], v[94:95], v[42:43] neg_lo:[0,0,1] neg_hi:[0,0,1]
	v_pk_fma_f32 v[86:87], v[36:37], v[94:95], v[44:45] neg_lo:[0,0,1] neg_hi:[0,0,1]
	v_pk_fma_f32 v[88:89], v[38:39], v[94:95], v[46:47] neg_lo:[0,0,1] neg_hi:[0,0,1]
	v_cvt_pk_bf16_f32 v90, v82, v83
	v_cvt_pk_bf16_f32 v91, v84, v85
	v_cvt_pk_bf16_f32 v92, v86, v87
	v_cvt_pk_bf16_f32 v93, v88, v89
	global_store_dwordx4 v48, v[90:93], s[22:23]
	s_add_u32 s22, s22, 0x1000
	s_addc_u32 s23, s23, 0
	s_cmp_lt_i32 s43, 7
	s_cbranch_scc1 .Lpl_sf_53
	v_pk_add_f32 v[32:33], v[32:33], v[66:67] neg_lo:[0,1] neg_hi:[0,1]
	v_pk_add_f32 v[34:35], v[34:35], v[68:69] neg_lo:[0,1] neg_hi:[0,1]
	v_pk_add_f32 v[36:37], v[36:37], v[70:71] neg_lo:[0,1] neg_hi:[0,1]
	v_pk_add_f32 v[38:39], v[38:39], v[72:73] neg_lo:[0,1] neg_hi:[0,1]
	s_branch .Lpl_se_54

.Lpl_se_54:
	v_lshlrev_b32_e32 v40, 16, v28
	v_and_b32_e32 v41, 0xffff0000, v28
	v_lshlrev_b32_e32 v42, 16, v29
	v_and_b32_e32 v43, 0xffff0000, v29
	v_lshlrev_b32_e32 v44, 16, v30
	v_and_b32_e32 v45, 0xffff0000, v30
	v_lshlrev_b32_e32 v46, 16, v31
	v_and_b32_e32 v47, 0xffff0000, v31
	v_pk_add_f32 v[32:33], v[32:33], v[40:41]
	v_pk_add_f32 v[34:35], v[34:35], v[42:43]
	v_pk_add_f32 v[36:37], v[36:37], v[44:45]
	v_pk_add_f32 v[38:39], v[38:39], v[46:47]
	v_pk_fma_f32 v[82:83], v[32:33], v[94:95], v[40:41] neg_lo:[0,0,1] neg_hi:[0,0,1]
	v_pk_fma_f32 v[84:85], v[34:35], v[94:95], v[42:43] neg_lo:[0,0,1] neg_hi:[0,0,1]
	v_pk_fma_f32 v[86:87], v[36:37], v[94:95], v[44:45] neg_lo:[0,0,1] neg_hi:[0,0,1]
	v_pk_fma_f32 v[88:89], v[38:39], v[94:95], v[46:47] neg_lo:[0,0,1] neg_hi:[0,0,1]
	v_cvt_pk_bf16_f32 v90, v82, v83
	v_cvt_pk_bf16_f32 v91, v84, v85
	v_cvt_pk_bf16_f32 v92, v86, v87
	v_cvt_pk_bf16_f32 v93, v88, v89
	global_store_dwordx4 v48, v[90:93], s[22:23]
	s_add_u32 s22, s22, 0x1000
	s_addc_u32 s23, s23, 0
	s_cmp_lt_i32 s43, 8
	s_cbranch_scc1 .Lpl_sf_55
	v_pk_add_f32 v[32:33], v[32:33], v[74:75] neg_lo:[0,1] neg_hi:[0,1]
	v_pk_add_f32 v[34:35], v[34:35], v[76:77] neg_lo:[0,1] neg_hi:[0,1]
	v_pk_add_f32 v[36:37], v[36:37], v[78:79] neg_lo:[0,1] neg_hi:[0,1]
	v_pk_add_f32 v[38:39], v[38:39], v[80:81] neg_lo:[0,1] neg_hi:[0,1]
	s_branch .Lpl_se_56

.Lpl_se_56:
.Lpl_done_15:
	s_waitcnt vmcnt(0)

	.amdhsa_kernel _Z10hybrid_fwdPKfS0_S0_S0_S0_S0_S0_S0_S0_S0_S0_S0_S0_S0_S0_S0_S0_S0_S0_S0_S0_S0_S0_PfPh4WTab
		.amdhsa_group_segment_fixed_size 0
		.amdhsa_private_segment_fixed_size 0
		.amdhsa_kernarg_size 1104
		.amdhsa_user_sgpr_count 2
		.amdhsa_user_sgpr_dispatch_ptr 0
		.amdhsa_user_sgpr_queue_ptr 0
		.amdhsa_user_sgpr_kernarg_segment_ptr 1
		.amdhsa_user_sgpr_dispatch_id 0
		.amdhsa_user_sgpr_kernarg_preload_length 0
		.amdhsa_user_sgpr_kernarg_preload_offset 0
		.amdhsa_user_sgpr_private_segment_size 0
		.amdhsa_uses_dynamic_stack 0
		.amdhsa_enable_private_segment 0
		.amdhsa_system_sgpr_workgroup_id_x 1
		.amdhsa_system_sgpr_workgroup_id_y 0
		.amdhsa_system_sgpr_workgroup_id_z 0
		.amdhsa_system_sgpr_workgroup_info 0
		.amdhsa_system_vgpr_workitem_id 2
		.amdhsa_next_free_vgpr 256
		.amdhsa_next_free_sgpr 102
		.amdhsa_accum_offset 256
		.amdhsa_reserve_vcc 1
		.amdhsa_float_round_mode_32 0
		.amdhsa_float_round_mode_16_64 0
		.amdhsa_float_denorm_mode_32 3
		.amdhsa_float_denorm_mode_16_64 3
		.amdhsa_dx10_clamp 1
		.amdhsa_ieee_mode 1
		.amdhsa_fp16_overflow 0
		.amdhsa_tg_split 0
		.amdhsa_exception_fp_ieee_invalid_op 0
		.amdhsa_exception_fp_denorm_src 0
		.amdhsa_exception_fp_ieee_div_zero 0
		.amdhsa_exception_fp_ieee_overflow 0
		.amdhsa_exception_fp_ieee_underflow 0
		.amdhsa_exception_fp_ieee_inexact 0
		.amdhsa_exception_int_div_zero 0
	.end_amdhsa_kernel

amdhsa.kernels:
  - .agpr_count:     0
    .args:
      - .address_space:  global
        .offset:         0
        .size:           8
        .value_kind:     global_buffer
      - .address_space:  global
        .offset:         8
        .size:           8
        .value_kind:     global_buffer
      - .address_space:  global
        .offset:         16
        .size:           8
        .value_kind:     global_buffer
      - .address_space:  global
        .offset:         24
        .size:           8
        .value_kind:     global_buffer
      - .address_space:  global
        .offset:         32
        .size:           8
        .value_kind:     global_buffer
      - .address_space:  global
        .offset:         40
        .size:           8
        .value_kind:     global_buffer
      - .address_space:  global
        .offset:         48
        .size:           8
        .value_kind:     global_buffer
      - .address_space:  global
        .offset:         56
        .size:           8
        .value_kind:     global_buffer
      - .address_space:  global
        .offset:         64
        .size:           8
        .value_kind:     global_buffer
      - .address_space:  global
        .offset:         72
        .size:           8
        .value_kind:     global_buffer
      - .address_space:  global
        .offset:         80
        .size:           8
        .value_kind:     global_buffer
      - .address_space:  global
        .offset:         88
        .size:           8
        .value_kind:     global_buffer
      - .address_space:  global
        .offset:         96
        .size:           8
        .value_kind:     global_buffer
      - .address_space:  global
        .offset:         104
        .size:           8
        .value_kind:     global_buffer
      - .address_space:  global
        .offset:         112
        .size:           8
        .value_kind:     global_buffer
      - .address_space:  global
        .offset:         120
        .size:           8
        .value_kind:     global_buffer
      - .address_space:  global
        .offset:         128
        .size:           8
        .value_kind:     global_buffer
      - .address_space:  global
        .offset:         136
        .size:           8
        .value_kind:     global_buffer
      - .address_space:  global
        .offset:         144
        .size:           8
        .value_kind:     global_buffer
      - .address_space:  global
        .offset:         152
        .size:           8
        .value_kind:     global_buffer
      - .address_space:  global
        .offset:         160
        .size:           8
        .value_kind:     global_buffer
      - .address_space:  global
        .offset:         168
        .size:           8
        .value_kind:     global_buffer
      - .address_space:  global
        .offset:         176
        .size:           8
        .value_kind:     global_buffer
      - .address_space:  global
        .offset:         184
        .size:           8
        .value_kind:     global_buffer
      - .address_space:  global
        .offset:         192
        .size:           8
        .value_kind:     global_buffer
      - .offset:         200
        .size:           648
        .value_kind:     by_value
      - .offset:         848
        .size:           4
        .value_kind:     hidden_block_count_x
      - .offset:         852
        .size:           4
        .value_kind:     hidden_block_count_y
      - .offset:         856
        .size:           4
        .value_kind:     hidden_block_count_z
      - .offset:         860
        .size:           2
        .value_kind:     hidden_group_size_x
      - .offset:         862
        .size:           2
        .value_kind:     hidden_group_size_y
      - .offset:         864
        .size:           2
        .value_kind:     hidden_group_size_z
      - .offset:         866
        .size:           2
        .value_kind:     hidden_remainder_x
      - .offset:         868
        .size:           2
        .value_kind:     hidden_remainder_y
      - .offset:         870
        .size:           2
        .value_kind:     hidden_remainder_z
      - .offset:         888
        .size:           8
        .value_kind:     hidden_global_offset_x
      - .offset:         896
        .size:           8
        .value_kind:     hidden_global_offset_y
      - .offset:         904
        .size:           8
        .value_kind:     hidden_global_offset_z
      - .offset:         912
        .size:           2
        .value_kind:     hidden_grid_dims
      - .offset:         936
        .size:           8
        .value_kind:     hidden_multigrid_sync_arg
      - .offset:         968
        .size:           4
        .value_kind:     hidden_dynamic_lds_size
    .group_segment_fixed_size: 0
    .kernarg_segment_align: 8
    .kernarg_segment_size: 1104
    .language:       OpenCL C
    .language_version:
      - 2
      - 0
    .max_flat_workgroup_size: 512
    .name:           _Z10hybrid_fwdPKfS0_S0_S0_S0_S0_S0_S0_S0_S0_S0_S0_S0_S0_S0_S0_S0_S0_S0_S0_S0_S0_S0_PfPh4WTab
    .private_segment_fixed_size: 0
    .sgpr_count:     108
    .sgpr_spill_count: 243
    .symbol:         _Z10hybrid_fwdPKfS0_S0_S0_S0_S0_S0_S0_S0_S0_S0_S0_S0_S0_S0_S0_S0_S0_S0_S0_S0_S0_S0_PfPh4WTab.kd
    .uniform_work_group_size: 1
    .uses_dynamic_stack: false
    .vgpr_count:     256
    .vgpr_spill_count: 0
    .wavefront_size: 64
